# plus: s_setprio pairs removed from the three GEMM K-loop bodies
# speedup vs baseline: 1.0039x; 1.0039x over previous
.Lc0s_first:
	s_add_i32 s62, s58, 0xfff80080
	s_and_b64 s[10:11], s[10:11], exec
	s_cselect_b32 s78, s54, s62
	s_cselect_b32 s62, s55, s60
	s_add_i32 s10, 0, 0x10000
	v_add_u32_e32 v0, s10, v157
	v_add_u32_e32 v147, s10, v158
	s_add_i32 s10, 0, 0x14000
	ds_read_b128 v[164:167], v0
	ds_read_b128 v[168:171], v0 offset:2048
	ds_read_b128 v[172:175], v147
	ds_read_b128 v[176:179], v147 offset:2048
	v_add_u32_e32 v0, s10, v157
	v_add_u32_e32 v147, s10, v158
	ds_read_b128 v[180:183], v0
	ds_read_b128 v[184:187], v0 offset:2048
	ds_read_b128 v[188:191], v147
	ds_read_b128 v[192:195], v147 offset:2048
	s_or_b32 s64, s78, 0x80
	s_or_b32 s65, s62, 0x80
	s_mov_b32 m0, s41
	ds_read_b128 v[196:199], v161
	ds_read_b128 v[204:207], v161 offset:2048
	ds_read_b128 v[208:211], v162
	ds_read_b128 v[212:215], v162 offset:2048
	ds_read_b128 v[216:219], v161 offset:4096
	ds_read_b128 v[220:223], v161 offset:6144
	ds_read_b128 v[224:227], v162 offset:4096
	ds_read_b128 v[228:231], v162 offset:6144
	buffer_load_dwordx4 v153, s[48:51], s58 offen lds
	s_mov_b32 m0, s42
	s_nop 0
	buffer_load_dwordx4 v155, s[48:51], s58 offen lds
	s_waitcnt vmcnt(8)
	s_waitcnt lgkmcnt(0)
	s_barrier
	s_waitcnt lgkmcnt(0)
	v_mfma_f32_16x16x32_f16 v[118:121], v[164:167], v[196:199], 0
	v_mfma_f32_16x16x32_f16 v[110:113], v[168:171], v[196:199], 0
	v_mfma_f32_16x16x32_f16 v[102:105], v[164:167], v[204:207], 0
	v_mfma_f32_16x16x32_f16 v[94:97], v[168:171], v[204:207], 0
	v_mfma_f32_16x16x32_f16 v[86:89], v[164:167], v[216:219], 0
	v_mfma_f32_16x16x32_f16 v[78:81], v[168:171], v[216:219], 0
	v_mfma_f32_16x16x32_f16 v[66:69], v[164:167], v[220:223], 0
	v_mfma_f32_16x16x32_f16 v[58:61], v[168:171], v[220:223], 0
	v_mfma_f32_16x16x32_f16 v[118:121], v[172:175], v[208:211], v[118:121]
	v_mfma_f32_16x16x32_f16 v[110:113], v[176:179], v[208:211], v[110:113]
	v_mfma_f32_16x16x32_f16 v[102:105], v[172:175], v[212:215], v[102:105]
	v_mfma_f32_16x16x32_f16 v[94:97], v[176:179], v[212:215], v[94:97]
	v_mfma_f32_16x16x32_f16 v[86:89], v[172:175], v[224:227], v[86:89]
	v_mfma_f32_16x16x32_f16 v[78:81], v[176:179], v[224:227], v[78:81]
	v_mfma_f32_16x16x32_f16 v[66:69], v[172:175], v[228:231], v[66:69]
	v_mfma_f32_16x16x32_f16 v[58:61], v[176:179], v[228:231], v[58:61]
	v_mfma_f32_16x16x32_f16 v[126:129], v[180:183], v[196:199], 0
	v_mfma_f32_16x16x32_f16 v[122:125], v[184:187], v[196:199], 0
	v_mfma_f32_16x16x32_f16 v[114:117], v[180:183], v[204:207], 0
	v_mfma_f32_16x16x32_f16 v[106:109], v[184:187], v[204:207], 0
	v_mfma_f32_16x16x32_f16 v[98:101], v[180:183], v[216:219], 0
	v_mfma_f32_16x16x32_f16 v[90:93], v[184:187], v[216:219], 0
	v_mfma_f32_16x16x32_f16 v[82:85], v[180:183], v[220:223], 0
	v_mfma_f32_16x16x32_f16 v[74:77], v[184:187], v[220:223], 0
	v_mfma_f32_16x16x32_f16 v[126:129], v[188:191], v[208:211], v[126:129]
	v_mfma_f32_16x16x32_f16 v[122:125], v[192:195], v[208:211], v[122:125]
	v_mfma_f32_16x16x32_f16 v[114:117], v[188:191], v[212:215], v[114:117]
	v_mfma_f32_16x16x32_f16 v[106:109], v[192:195], v[212:215], v[106:109]
	v_mfma_f32_16x16x32_f16 v[98:101], v[188:191], v[224:227], v[98:101]
	v_mfma_f32_16x16x32_f16 v[90:93], v[192:195], v[224:227], v[90:93]
	v_mfma_f32_16x16x32_f16 v[82:85], v[188:191], v[228:231], v[82:85]
	v_mfma_f32_16x16x32_f16 v[74:77], v[192:195], v[228:231], v[74:77]
	s_barrier
	s_mov_b32 m0, s26
	s_mov_b32 s10, s50
	s_mov_b32 s11, s51
	ds_read_b128 v[196:199], v161 offset:16384
	ds_read_b128 v[204:207], v161 offset:18432
	ds_read_b128 v[208:211], v162 offset:16384
	ds_read_b128 v[212:215], v162 offset:18432
	ds_read_b128 v[216:219], v161 offset:20480
	ds_read_b128 v[220:223], v161 offset:22528
	ds_read_b128 v[224:227], v162 offset:20480
	ds_read_b128 v[228:231], v162 offset:22528
	buffer_load_dwordx4 v154, s[8:11], s62 offen lds
	s_mov_b32 m0, s27
	s_add_i32 s81, s62, 0x80000
	buffer_load_dwordx4 v156, s[8:11], s62 offen lds
	s_mov_b32 m0, s28
	s_nop 0
	buffer_load_dwordx4 v154, s[8:11], s81 offen lds
	s_mov_b32 m0, s29
	s_nop 0
	buffer_load_dwordx4 v156, s[8:11], s81 offen lds
	s_mov_b32 m0, s3
	s_nop 0
	buffer_load_dwordx4 v153, s[48:51], s78 offen lds
	s_mov_b32 m0, s30
	s_nop 0
	buffer_load_dwordx4 v155, s[48:51], s78 offen lds
	s_waitcnt vmcnt(8)
	s_waitcnt lgkmcnt(0)
	s_barrier
	s_waitcnt lgkmcnt(0)
	v_mfma_f32_16x16x32_f16 v[54:57], v[164:167], v[196:199], 0
	v_mfma_f32_16x16x32_f16 v[46:49], v[168:171], v[196:199], 0
	v_mfma_f32_16x16x32_f16 v[38:41], v[164:167], v[204:207], 0
	v_mfma_f32_16x16x32_f16 v[30:33], v[168:171], v[204:207], 0
	v_mfma_f32_16x16x32_f16 v[22:25], v[164:167], v[216:219], 0
	v_mfma_f32_16x16x32_f16 v[14:17], v[168:171], v[216:219], 0
	v_mfma_f32_16x16x32_f16 v[6:9], v[164:167], v[220:223], 0
	v_mfma_f32_16x16x32_f16 v[2:5], v[168:171], v[220:223], 0
	v_mfma_f32_16x16x32_f16 v[54:57], v[172:175], v[208:211], v[54:57]
	v_mfma_f32_16x16x32_f16 v[46:49], v[176:179], v[208:211], v[46:49]
	v_mfma_f32_16x16x32_f16 v[38:41], v[172:175], v[212:215], v[38:41]
	v_mfma_f32_16x16x32_f16 v[30:33], v[176:179], v[212:215], v[30:33]
	v_mfma_f32_16x16x32_f16 v[22:25], v[172:175], v[224:227], v[22:25]
	v_mfma_f32_16x16x32_f16 v[14:17], v[176:179], v[224:227], v[14:17]
	v_mfma_f32_16x16x32_f16 v[6:9], v[172:175], v[228:231], v[6:9]
	v_mfma_f32_16x16x32_f16 v[2:5], v[176:179], v[228:231], v[2:5]
	v_mfma_f32_16x16x32_f16 v[70:73], v[180:183], v[196:199], 0
	v_mfma_f32_16x16x32_f16 v[62:65], v[184:187], v[196:199], 0
	v_mfma_f32_16x16x32_f16 v[50:53], v[180:183], v[204:207], 0
	v_mfma_f32_16x16x32_f16 v[42:45], v[184:187], v[204:207], 0
	v_mfma_f32_16x16x32_f16 v[34:37], v[180:183], v[216:219], 0
	v_mfma_f32_16x16x32_f16 v[26:29], v[184:187], v[216:219], 0
	v_mfma_f32_16x16x32_f16 v[18:21], v[180:183], v[220:223], 0
	v_mfma_f32_16x16x32_f16 v[10:13], v[184:187], v[220:223], 0
	v_mfma_f32_16x16x32_f16 v[70:73], v[188:191], v[208:211], v[70:73]
	v_mfma_f32_16x16x32_f16 v[62:65], v[192:195], v[208:211], v[62:65]
	v_mfma_f32_16x16x32_f16 v[50:53], v[188:191], v[212:215], v[50:53]
	v_mfma_f32_16x16x32_f16 v[42:45], v[192:195], v[212:215], v[42:45]
	v_mfma_f32_16x16x32_f16 v[34:37], v[188:191], v[224:227], v[34:37]
	v_mfma_f32_16x16x32_f16 v[26:29], v[192:195], v[224:227], v[26:29]
	v_mfma_f32_16x16x32_f16 v[18:21], v[188:191], v[228:231], v[18:21]
	v_mfma_f32_16x16x32_f16 v[10:13], v[192:195], v[228:231], v[10:13]
	s_barrier
	s_add_i32 s81, 0, 0x18000
	v_add_u32_e32 v0, s81, v157
	v_add_u32_e32 v147, s81, v158
	s_add_i32 s81, 0, 0x1c000
	ds_read_b128 v[164:167], v0
	ds_read_b128 v[168:171], v0 offset:2048
	ds_read_b128 v[172:175], v147
	ds_read_b128 v[176:179], v147 offset:2048
	v_add_u32_e32 v0, s81, v157
	v_add_u32_e32 v147, s81, v158
	ds_read_b128 v[180:183], v0
	ds_read_b128 v[184:187], v0 offset:2048
	ds_read_b128 v[188:191], v147
	ds_read_b128 v[192:195], v147 offset:2048
	s_add_i32 s78, s78, 0x80000
	s_mov_b32 m0, s31
	ds_read_b128 v[196:199], v161 offset:32768
	ds_read_b128 v[204:207], v161 offset:34816
	ds_read_b128 v[208:211], v162 offset:32768
	ds_read_b128 v[212:215], v162 offset:34816
	ds_read_b128 v[216:219], v161 offset:36864
	ds_read_b128 v[220:223], v161 offset:38912
	ds_read_b128 v[224:227], v162 offset:36864
	ds_read_b128 v[228:231], v162 offset:38912
	buffer_load_dwordx4 v153, s[48:51], s78 offen lds
	s_mov_b32 m0, s34
	s_nop 0
	buffer_load_dwordx4 v155, s[48:51], s78 offen lds
	s_waitcnt vmcnt(8)
	s_waitcnt lgkmcnt(0)
	s_barrier
	s_waitcnt lgkmcnt(0)
	v_mfma_f32_16x16x32_f16 v[118:121], v[164:167], v[196:199], v[118:121]
	v_mfma_f32_16x16x32_f16 v[110:113], v[168:171], v[196:199], v[110:113]
	v_mfma_f32_16x16x32_f16 v[102:105], v[164:167], v[204:207], v[102:105]
	v_mfma_f32_16x16x32_f16 v[94:97], v[168:171], v[204:207], v[94:97]
	v_mfma_f32_16x16x32_f16 v[86:89], v[164:167], v[216:219], v[86:89]
	v_mfma_f32_16x16x32_f16 v[78:81], v[168:171], v[216:219], v[78:81]
	v_mfma_f32_16x16x32_f16 v[66:69], v[164:167], v[220:223], v[66:69]
	v_mfma_f32_16x16x32_f16 v[58:61], v[168:171], v[220:223], v[58:61]
	v_mfma_f32_16x16x32_f16 v[118:121], v[172:175], v[208:211], v[118:121]
	v_mfma_f32_16x16x32_f16 v[110:113], v[176:179], v[208:211], v[110:113]
	v_mfma_f32_16x16x32_f16 v[102:105], v[172:175], v[212:215], v[102:105]
	v_mfma_f32_16x16x32_f16 v[94:97], v[176:179], v[212:215], v[94:97]
	v_mfma_f32_16x16x32_f16 v[86:89], v[172:175], v[224:227], v[86:89]
	v_mfma_f32_16x16x32_f16 v[78:81], v[176:179], v[224:227], v[78:81]
	v_mfma_f32_16x16x32_f16 v[66:69], v[172:175], v[228:231], v[66:69]
	v_mfma_f32_16x16x32_f16 v[58:61], v[176:179], v[228:231], v[58:61]
	v_mfma_f32_16x16x32_f16 v[126:129], v[180:183], v[196:199], v[126:129]
	v_mfma_f32_16x16x32_f16 v[122:125], v[184:187], v[196:199], v[122:125]
	v_mfma_f32_16x16x32_f16 v[114:117], v[180:183], v[204:207], v[114:117]
	v_mfma_f32_16x16x32_f16 v[106:109], v[184:187], v[204:207], v[106:109]
	v_mfma_f32_16x16x32_f16 v[98:101], v[180:183], v[216:219], v[98:101]
	v_mfma_f32_16x16x32_f16 v[90:93], v[184:187], v[216:219], v[90:93]
	v_mfma_f32_16x16x32_f16 v[82:85], v[180:183], v[220:223], v[82:85]
	v_mfma_f32_16x16x32_f16 v[74:77], v[184:187], v[220:223], v[74:77]
	v_mfma_f32_16x16x32_f16 v[126:129], v[188:191], v[208:211], v[126:129]
	v_mfma_f32_16x16x32_f16 v[122:125], v[192:195], v[208:211], v[122:125]
	v_mfma_f32_16x16x32_f16 v[114:117], v[188:191], v[212:215], v[114:117]
	v_mfma_f32_16x16x32_f16 v[106:109], v[192:195], v[212:215], v[106:109]
	v_mfma_f32_16x16x32_f16 v[98:101], v[188:191], v[224:227], v[98:101]
	v_mfma_f32_16x16x32_f16 v[90:93], v[192:195], v[224:227], v[90:93]
	v_mfma_f32_16x16x32_f16 v[82:85], v[188:191], v[228:231], v[82:85]
	v_mfma_f32_16x16x32_f16 v[74:77], v[192:195], v[228:231], v[74:77]
	s_barrier
	s_mov_b32 m0, s35
	ds_read_b128 v[196:199], v161 offset:49152
	ds_read_b128 v[204:207], v161 offset:51200
	ds_read_b128 v[208:211], v162 offset:49152
	ds_read_b128 v[212:215], v162 offset:51200
	ds_read_b128 v[216:219], v161 offset:53248
	ds_read_b128 v[220:223], v161 offset:55296
	ds_read_b128 v[224:227], v162 offset:53248
	ds_read_b128 v[228:231], v162 offset:55296
	buffer_load_dwordx4 v154, s[8:11], s65 offen lds
	s_mov_b32 m0, s36
	s_add_i32 s62, s62, 0x80080
	buffer_load_dwordx4 v156, s[8:11], s65 offen lds
	s_mov_b32 m0, s39
	s_nop 0
	buffer_load_dwordx4 v154, s[8:11], s62 offen lds
	s_mov_b32 m0, s40
	s_nop 0
	buffer_load_dwordx4 v156, s[8:11], s62 offen lds
	s_mov_b32 m0, s37
	s_nop 0
	buffer_load_dwordx4 v153, s[48:51], s64 offen lds
	s_mov_b32 m0, s38
	s_nop 0
	buffer_load_dwordx4 v155, s[48:51], s64 offen lds
	s_waitcnt vmcnt(8)
	s_waitcnt lgkmcnt(0)
	s_barrier
	s_waitcnt lgkmcnt(0)
	v_mfma_f32_16x16x32_f16 v[54:57], v[164:167], v[196:199], v[54:57]
	v_mfma_f32_16x16x32_f16 v[46:49], v[168:171], v[196:199], v[46:49]
	v_mfma_f32_16x16x32_f16 v[38:41], v[164:167], v[204:207], v[38:41]
	v_mfma_f32_16x16x32_f16 v[30:33], v[168:171], v[204:207], v[30:33]
	v_mfma_f32_16x16x32_f16 v[22:25], v[164:167], v[216:219], v[22:25]
	v_mfma_f32_16x16x32_f16 v[14:17], v[168:171], v[216:219], v[14:17]
	v_mfma_f32_16x16x32_f16 v[6:9], v[164:167], v[220:223], v[6:9]
	v_mfma_f32_16x16x32_f16 v[2:5], v[168:171], v[220:223], v[2:5]
	v_mfma_f32_16x16x32_f16 v[54:57], v[172:175], v[208:211], v[54:57]
	v_mfma_f32_16x16x32_f16 v[46:49], v[176:179], v[208:211], v[46:49]
	v_mfma_f32_16x16x32_f16 v[38:41], v[172:175], v[212:215], v[38:41]
	v_mfma_f32_16x16x32_f16 v[30:33], v[176:179], v[212:215], v[30:33]
	v_mfma_f32_16x16x32_f16 v[22:25], v[172:175], v[224:227], v[22:25]
	v_mfma_f32_16x16x32_f16 v[14:17], v[176:179], v[224:227], v[14:17]
	v_mfma_f32_16x16x32_f16 v[6:9], v[172:175], v[228:231], v[6:9]
	v_mfma_f32_16x16x32_f16 v[2:5], v[176:179], v[228:231], v[2:5]
	v_mfma_f32_16x16x32_f16 v[70:73], v[180:183], v[196:199], v[70:73]
	v_mfma_f32_16x16x32_f16 v[62:65], v[184:187], v[196:199], v[62:65]
	v_mfma_f32_16x16x32_f16 v[50:53], v[180:183], v[204:207], v[50:53]
	v_mfma_f32_16x16x32_f16 v[42:45], v[184:187], v[204:207], v[42:45]
	v_mfma_f32_16x16x32_f16 v[34:37], v[180:183], v[216:219], v[34:37]
	v_mfma_f32_16x16x32_f16 v[26:29], v[184:187], v[216:219], v[26:29]
	v_mfma_f32_16x16x32_f16 v[18:21], v[180:183], v[220:223], v[18:21]
	v_mfma_f32_16x16x32_f16 v[10:13], v[184:187], v[220:223], v[10:13]
	v_mfma_f32_16x16x32_f16 v[70:73], v[188:191], v[208:211], v[70:73]
	v_mfma_f32_16x16x32_f16 v[62:65], v[192:195], v[208:211], v[62:65]
	v_mfma_f32_16x16x32_f16 v[50:53], v[188:191], v[212:215], v[50:53]
	v_mfma_f32_16x16x32_f16 v[42:45], v[192:195], v[212:215], v[42:45]
	v_mfma_f32_16x16x32_f16 v[34:37], v[188:191], v[224:227], v[34:37]
	v_mfma_f32_16x16x32_f16 v[26:29], v[192:195], v[224:227], v[26:29]
	v_mfma_f32_16x16x32_f16 v[18:21], v[188:191], v[228:231], v[18:21]
	v_mfma_f32_16x16x32_f16 v[10:13], v[192:195], v[228:231], v[10:13]
	s_barrier
	s_branch .Lc0s_tail
.Lc0s_final:
	s_add_i32 s62, s58, 0xfff80080
	s_and_b64 s[10:11], s[10:11], exec
	s_cselect_b32 s78, s54, s62
	s_cselect_b32 s62, s55, s60
	s_add_i32 s10, 0, 0x10000
	v_add_u32_e32 v0, s10, v157
	v_add_u32_e32 v147, s10, v158
	s_add_i32 s10, 0, 0x14000
	ds_read_b128 v[164:167], v0
	ds_read_b128 v[168:171], v0 offset:2048
	ds_read_b128 v[172:175], v147
	ds_read_b128 v[176:179], v147 offset:2048
	v_add_u32_e32 v0, s10, v157
	v_add_u32_e32 v147, s10, v158
	ds_read_b128 v[180:183], v0
	ds_read_b128 v[184:187], v0 offset:2048
	ds_read_b128 v[188:191], v147
	ds_read_b128 v[192:195], v147 offset:2048
	s_or_b32 s64, s78, 0x80
	s_or_b32 s65, s62, 0x80
	s_mov_b32 m0, s41
	ds_read_b128 v[196:199], v161
	ds_read_b128 v[204:207], v161 offset:2048
	ds_read_b128 v[208:211], v162
	ds_read_b128 v[212:215], v162 offset:2048
	ds_read_b128 v[216:219], v161 offset:4096
	ds_read_b128 v[220:223], v161 offset:6144
	ds_read_b128 v[224:227], v162 offset:4096
	ds_read_b128 v[228:231], v162 offset:6144
	buffer_load_dwordx4 v153, s[48:51], s58 offen lds
	s_mov_b32 m0, s42
	s_nop 0
	buffer_load_dwordx4 v155, s[48:51], s58 offen lds
	s_waitcnt vmcnt(8)
	s_waitcnt lgkmcnt(0)
	s_barrier
	s_waitcnt lgkmcnt(0)
	v_mfma_f32_16x16x32_f16 v[118:121], v[164:167], v[196:199], v[118:121]
	v_mfma_f32_16x16x32_f16 v[110:113], v[168:171], v[196:199], v[110:113]
	v_mfma_f32_16x16x32_f16 v[102:105], v[164:167], v[204:207], v[102:105]
	v_mfma_f32_16x16x32_f16 v[94:97], v[168:171], v[204:207], v[94:97]
	v_mfma_f32_16x16x32_f16 v[86:89], v[164:167], v[216:219], v[86:89]
	v_mfma_f32_16x16x32_f16 v[78:81], v[168:171], v[216:219], v[78:81]
	v_mfma_f32_16x16x32_f16 v[66:69], v[164:167], v[220:223], v[66:69]
	v_mfma_f32_16x16x32_f16 v[58:61], v[168:171], v[220:223], v[58:61]
	v_mfma_f32_16x16x32_f16 v[118:121], v[172:175], v[208:211], v[118:121]
	v_mfma_f32_16x16x32_f16 v[110:113], v[176:179], v[208:211], v[110:113]
	v_mfma_f32_16x16x32_f16 v[102:105], v[172:175], v[212:215], v[102:105]
	v_mfma_f32_16x16x32_f16 v[94:97], v[176:179], v[212:215], v[94:97]
	v_mfma_f32_16x16x32_f16 v[86:89], v[172:175], v[224:227], v[86:89]
	v_mfma_f32_16x16x32_f16 v[78:81], v[176:179], v[224:227], v[78:81]
	v_mfma_f32_16x16x32_f16 v[66:69], v[172:175], v[228:231], v[66:69]
	v_mfma_f32_16x16x32_f16 v[58:61], v[176:179], v[228:231], v[58:61]
	v_mfma_f32_16x16x32_f16 v[126:129], v[180:183], v[196:199], v[126:129]
	v_mfma_f32_16x16x32_f16 v[122:125], v[184:187], v[196:199], v[122:125]
	v_mfma_f32_16x16x32_f16 v[114:117], v[180:183], v[204:207], v[114:117]
	v_mfma_f32_16x16x32_f16 v[106:109], v[184:187], v[204:207], v[106:109]
	v_mfma_f32_16x16x32_f16 v[98:101], v[180:183], v[216:219], v[98:101]
	v_mfma_f32_16x16x32_f16 v[90:93], v[184:187], v[216:219], v[90:93]
	v_mfma_f32_16x16x32_f16 v[82:85], v[180:183], v[220:223], v[82:85]
	v_mfma_f32_16x16x32_f16 v[74:77], v[184:187], v[220:223], v[74:77]
	v_mfma_f32_16x16x32_f16 v[126:129], v[188:191], v[208:211], v[126:129]
	v_mfma_f32_16x16x32_f16 v[122:125], v[192:195], v[208:211], v[122:125]
	v_mfma_f32_16x16x32_f16 v[114:117], v[188:191], v[212:215], v[114:117]
	v_mfma_f32_16x16x32_f16 v[106:109], v[192:195], v[212:215], v[106:109]
	v_mfma_f32_16x16x32_f16 v[98:101], v[188:191], v[224:227], v[98:101]
	v_mfma_f32_16x16x32_f16 v[90:93], v[192:195], v[224:227], v[90:93]
	v_mfma_f32_16x16x32_f16 v[82:85], v[188:191], v[228:231], v[82:85]
	v_mfma_f32_16x16x32_f16 v[74:77], v[192:195], v[228:231], v[74:77]
	s_barrier
	s_mov_b32 s10, s50
	s_mov_b32 s11, s51
	ds_read_b128 v[196:199], v161 offset:16384
	ds_read_b128 v[204:207], v161 offset:18432
	ds_read_b128 v[208:211], v162 offset:16384
	ds_read_b128 v[212:215], v162 offset:18432
	ds_read_b128 v[216:219], v161 offset:20480
	ds_read_b128 v[220:223], v161 offset:22528
	ds_read_b128 v[224:227], v162 offset:20480
	ds_read_b128 v[228:231], v162 offset:22528
	s_add_i32 s81, s62, 0x80000
	s_waitcnt vmcnt(2)
	s_waitcnt lgkmcnt(0)
	s_barrier
	s_waitcnt lgkmcnt(0)
	v_mfma_f32_16x16x32_f16 v[54:57], v[164:167], v[196:199], v[54:57]
	v_mfma_f32_16x16x32_f16 v[46:49], v[168:171], v[196:199], v[46:49]
	v_mfma_f32_16x16x32_f16 v[38:41], v[164:167], v[204:207], v[38:41]
	v_mfma_f32_16x16x32_f16 v[30:33], v[168:171], v[204:207], v[30:33]
	v_mfma_f32_16x16x32_f16 v[22:25], v[164:167], v[216:219], v[22:25]
	v_mfma_f32_16x16x32_f16 v[14:17], v[168:171], v[216:219], v[14:17]
	v_mfma_f32_16x16x32_f16 v[6:9], v[164:167], v[220:223], v[6:9]
	v_mfma_f32_16x16x32_f16 v[2:5], v[168:171], v[220:223], v[2:5]
	v_mfma_f32_16x16x32_f16 v[54:57], v[172:175], v[208:211], v[54:57]
	v_mfma_f32_16x16x32_f16 v[46:49], v[176:179], v[208:211], v[46:49]
	v_mfma_f32_16x16x32_f16 v[38:41], v[172:175], v[212:215], v[38:41]
	v_mfma_f32_16x16x32_f16 v[30:33], v[176:179], v[212:215], v[30:33]
	v_mfma_f32_16x16x32_f16 v[22:25], v[172:175], v[224:227], v[22:25]
	v_mfma_f32_16x16x32_f16 v[14:17], v[176:179], v[224:227], v[14:17]
	v_mfma_f32_16x16x32_f16 v[6:9], v[172:175], v[228:231], v[6:9]
	v_mfma_f32_16x16x32_f16 v[2:5], v[176:179], v[228:231], v[2:5]
	v_mfma_f32_16x16x32_f16 v[70:73], v[180:183], v[196:199], v[70:73]
	v_mfma_f32_16x16x32_f16 v[62:65], v[184:187], v[196:199], v[62:65]
	v_mfma_f32_16x16x32_f16 v[50:53], v[180:183], v[204:207], v[50:53]
	v_mfma_f32_16x16x32_f16 v[42:45], v[184:187], v[204:207], v[42:45]
	v_mfma_f32_16x16x32_f16 v[34:37], v[180:183], v[216:219], v[34:37]
	v_mfma_f32_16x16x32_f16 v[26:29], v[184:187], v[216:219], v[26:29]
	v_mfma_f32_16x16x32_f16 v[18:21], v[180:183], v[220:223], v[18:21]
	v_mfma_f32_16x16x32_f16 v[10:13], v[184:187], v[220:223], v[10:13]
	v_mfma_f32_16x16x32_f16 v[70:73], v[188:191], v[208:211], v[70:73]
	v_mfma_f32_16x16x32_f16 v[62:65], v[192:195], v[208:211], v[62:65]
	v_mfma_f32_16x16x32_f16 v[50:53], v[188:191], v[212:215], v[50:53]
	v_mfma_f32_16x16x32_f16 v[42:45], v[192:195], v[212:215], v[42:45]
	v_mfma_f32_16x16x32_f16 v[34:37], v[188:191], v[224:227], v[34:37]
	v_mfma_f32_16x16x32_f16 v[26:29], v[192:195], v[224:227], v[26:29]
	v_mfma_f32_16x16x32_f16 v[18:21], v[188:191], v[228:231], v[18:21]
	v_mfma_f32_16x16x32_f16 v[10:13], v[192:195], v[228:231], v[10:13]
	s_barrier
	s_add_i32 s81, 0, 0x18000
	v_add_u32_e32 v0, s81, v157
	v_add_u32_e32 v147, s81, v158
	s_add_i32 s81, 0, 0x1c000
	ds_read_b128 v[164:167], v0
	ds_read_b128 v[168:171], v0 offset:2048
	ds_read_b128 v[172:175], v147
	ds_read_b128 v[176:179], v147 offset:2048
	v_add_u32_e32 v0, s81, v157
	v_add_u32_e32 v147, s81, v158
	ds_read_b128 v[180:183], v0
	ds_read_b128 v[184:187], v0 offset:2048
	ds_read_b128 v[188:191], v147
	ds_read_b128 v[192:195], v147 offset:2048
	s_add_i32 s78, s78, 0x80000
	ds_read_b128 v[196:199], v161 offset:32768
	ds_read_b128 v[204:207], v161 offset:34816
	ds_read_b128 v[208:211], v162 offset:32768
	ds_read_b128 v[212:215], v162 offset:34816
	ds_read_b128 v[216:219], v161 offset:36864
	ds_read_b128 v[220:223], v161 offset:38912
	ds_read_b128 v[224:227], v162 offset:36864
	ds_read_b128 v[228:231], v162 offset:38912
	s_waitcnt vmcnt(0)
	s_waitcnt lgkmcnt(0)
	s_barrier
	s_waitcnt lgkmcnt(0)
	v_mfma_f32_16x16x32_f16 v[118:121], v[164:167], v[196:199], v[118:121]
	v_mfma_f32_16x16x32_f16 v[110:113], v[168:171], v[196:199], v[110:113]
	v_mfma_f32_16x16x32_f16 v[102:105], v[164:167], v[204:207], v[102:105]
	v_mfma_f32_16x16x32_f16 v[94:97], v[168:171], v[204:207], v[94:97]
	v_mfma_f32_16x16x32_f16 v[86:89], v[164:167], v[216:219], v[86:89]
	v_mfma_f32_16x16x32_f16 v[78:81], v[168:171], v[216:219], v[78:81]
	v_mfma_f32_16x16x32_f16 v[66:69], v[164:167], v[220:223], v[66:69]
	v_mfma_f32_16x16x32_f16 v[58:61], v[168:171], v[220:223], v[58:61]
	v_mfma_f32_16x16x32_f16 v[118:121], v[172:175], v[208:211], v[118:121]
	v_mfma_f32_16x16x32_f16 v[110:113], v[176:179], v[208:211], v[110:113]
	v_mfma_f32_16x16x32_f16 v[102:105], v[172:175], v[212:215], v[102:105]
	v_mfma_f32_16x16x32_f16 v[94:97], v[176:179], v[212:215], v[94:97]
	v_mfma_f32_16x16x32_f16 v[86:89], v[172:175], v[224:227], v[86:89]
	v_mfma_f32_16x16x32_f16 v[78:81], v[176:179], v[224:227], v[78:81]
	v_mfma_f32_16x16x32_f16 v[66:69], v[172:175], v[228:231], v[66:69]
	v_mfma_f32_16x16x32_f16 v[58:61], v[176:179], v[228:231], v[58:61]
	v_mfma_f32_16x16x32_f16 v[126:129], v[180:183], v[196:199], v[126:129]
	v_mfma_f32_16x16x32_f16 v[122:125], v[184:187], v[196:199], v[122:125]
	v_mfma_f32_16x16x32_f16 v[114:117], v[180:183], v[204:207], v[114:117]
	v_mfma_f32_16x16x32_f16 v[106:109], v[184:187], v[204:207], v[106:109]
	v_mfma_f32_16x16x32_f16 v[98:101], v[180:183], v[216:219], v[98:101]
	v_mfma_f32_16x16x32_f16 v[90:93], v[184:187], v[216:219], v[90:93]
	v_mfma_f32_16x16x32_f16 v[82:85], v[180:183], v[220:223], v[82:85]
	v_mfma_f32_16x16x32_f16 v[74:77], v[184:187], v[220:223], v[74:77]
	v_mfma_f32_16x16x32_f16 v[126:129], v[188:191], v[208:211], v[126:129]
	v_mfma_f32_16x16x32_f16 v[122:125], v[192:195], v[208:211], v[122:125]
	v_mfma_f32_16x16x32_f16 v[114:117], v[188:191], v[212:215], v[114:117]
	v_mfma_f32_16x16x32_f16 v[106:109], v[192:195], v[212:215], v[106:109]
	v_mfma_f32_16x16x32_f16 v[98:101], v[188:191], v[224:227], v[98:101]
	v_mfma_f32_16x16x32_f16 v[90:93], v[192:195], v[224:227], v[90:93]
	v_mfma_f32_16x16x32_f16 v[82:85], v[188:191], v[228:231], v[82:85]
	v_mfma_f32_16x16x32_f16 v[74:77], v[192:195], v[228:231], v[74:77]
	s_barrier
	ds_read_b128 v[196:199], v161 offset:49152
	ds_read_b128 v[204:207], v161 offset:51200
	ds_read_b128 v[208:211], v162 offset:49152
	ds_read_b128 v[212:215], v162 offset:51200
	ds_read_b128 v[216:219], v161 offset:53248
	ds_read_b128 v[220:223], v161 offset:55296
	ds_read_b128 v[224:227], v162 offset:53248
	ds_read_b128 v[228:231], v162 offset:55296
	s_add_i32 s62, s62, 0x80080
	s_waitcnt vmcnt(0)
	s_waitcnt lgkmcnt(0)
	s_barrier
	s_waitcnt lgkmcnt(0)
	v_mfma_f32_16x16x32_f16 v[54:57], v[164:167], v[196:199], v[54:57]
	v_mfma_f32_16x16x32_f16 v[46:49], v[168:171], v[196:199], v[46:49]
	v_mfma_f32_16x16x32_f16 v[38:41], v[164:167], v[204:207], v[38:41]
	v_mfma_f32_16x16x32_f16 v[30:33], v[168:171], v[204:207], v[30:33]
	v_mfma_f32_16x16x32_f16 v[22:25], v[164:167], v[216:219], v[22:25]
	v_mfma_f32_16x16x32_f16 v[14:17], v[168:171], v[216:219], v[14:17]
	v_mfma_f32_16x16x32_f16 v[6:9], v[164:167], v[220:223], v[6:9]
	v_mfma_f32_16x16x32_f16 v[2:5], v[168:171], v[220:223], v[2:5]
	v_mfma_f32_16x16x32_f16 v[54:57], v[172:175], v[208:211], v[54:57]
	v_mfma_f32_16x16x32_f16 v[46:49], v[176:179], v[208:211], v[46:49]
	v_mfma_f32_16x16x32_f16 v[38:41], v[172:175], v[212:215], v[38:41]
	v_mfma_f32_16x16x32_f16 v[30:33], v[176:179], v[212:215], v[30:33]
	v_mfma_f32_16x16x32_f16 v[22:25], v[172:175], v[224:227], v[22:25]
	v_mfma_f32_16x16x32_f16 v[14:17], v[176:179], v[224:227], v[14:17]
	v_mfma_f32_16x16x32_f16 v[6:9], v[172:175], v[228:231], v[6:9]
	v_mfma_f32_16x16x32_f16 v[2:5], v[176:179], v[228:231], v[2:5]
	v_mfma_f32_16x16x32_f16 v[70:73], v[180:183], v[196:199], v[70:73]
	v_mfma_f32_16x16x32_f16 v[62:65], v[184:187], v[196:199], v[62:65]
	v_mfma_f32_16x16x32_f16 v[50:53], v[180:183], v[204:207], v[50:53]
	v_mfma_f32_16x16x32_f16 v[42:45], v[184:187], v[204:207], v[42:45]
	v_mfma_f32_16x16x32_f16 v[34:37], v[180:183], v[216:219], v[34:37]
	v_mfma_f32_16x16x32_f16 v[26:29], v[184:187], v[216:219], v[26:29]
	v_mfma_f32_16x16x32_f16 v[18:21], v[180:183], v[220:223], v[18:21]
	v_mfma_f32_16x16x32_f16 v[10:13], v[184:187], v[220:223], v[10:13]
	v_mfma_f32_16x16x32_f16 v[70:73], v[188:191], v[208:211], v[70:73]
	v_mfma_f32_16x16x32_f16 v[62:65], v[192:195], v[208:211], v[62:65]
	v_mfma_f32_16x16x32_f16 v[50:53], v[188:191], v[212:215], v[50:53]
	v_mfma_f32_16x16x32_f16 v[42:45], v[192:195], v[212:215], v[42:45]
	v_mfma_f32_16x16x32_f16 v[34:37], v[188:191], v[224:227], v[34:37]
	v_mfma_f32_16x16x32_f16 v[26:29], v[192:195], v[224:227], v[26:29]
	v_mfma_f32_16x16x32_f16 v[18:21], v[188:191], v[228:231], v[18:21]
	v_mfma_f32_16x16x32_f16 v[10:13], v[192:195], v[228:231], v[10:13]
	s_barrier
	s_branch .Lc0s_tail

.Lc0s_norm:
	s_add_i32 s62, s58, 0xfff80080
	s_and_b64 s[10:11], s[10:11], exec
	s_cselect_b32 s78, s54, s62
	s_cselect_b32 s62, s55, s60
	s_add_i32 s10, 0, 0x10000
	v_add_u32_e32 v0, s10, v157
	v_add_u32_e32 v147, s10, v158
	s_add_i32 s10, 0, 0x14000
	ds_read_b128 v[164:167], v0
	ds_read_b128 v[168:171], v0 offset:2048
	ds_read_b128 v[172:175], v147
	ds_read_b128 v[176:179], v147 offset:2048
	v_add_u32_e32 v0, s10, v157
	v_add_u32_e32 v147, s10, v158
	ds_read_b128 v[180:183], v0
	ds_read_b128 v[184:187], v0 offset:2048
	ds_read_b128 v[188:191], v147
	ds_read_b128 v[192:195], v147 offset:2048
	s_or_b32 s64, s78, 0x80
	s_or_b32 s65, s62, 0x80
	s_mov_b32 m0, s41
	ds_read_b128 v[196:199], v161
	ds_read_b128 v[204:207], v161 offset:2048
	ds_read_b128 v[208:211], v162
	ds_read_b128 v[212:215], v162 offset:2048
	ds_read_b128 v[216:219], v161 offset:4096
	ds_read_b128 v[220:223], v161 offset:6144
	ds_read_b128 v[224:227], v162 offset:4096
	ds_read_b128 v[228:231], v162 offset:6144
	buffer_load_dwordx4 v153, s[48:51], s58 offen lds
	s_mov_b32 m0, s42
	s_nop 0
	buffer_load_dwordx4 v155, s[48:51], s58 offen lds
	s_waitcnt vmcnt(8)
	s_waitcnt lgkmcnt(0)
	s_barrier
	s_waitcnt lgkmcnt(0)
	v_mfma_f32_16x16x32_f16 v[118:121], v[164:167], v[196:199], v[118:121]
	v_mfma_f32_16x16x32_f16 v[110:113], v[168:171], v[196:199], v[110:113]
	v_mfma_f32_16x16x32_f16 v[102:105], v[164:167], v[204:207], v[102:105]
	v_mfma_f32_16x16x32_f16 v[94:97], v[168:171], v[204:207], v[94:97]
	v_mfma_f32_16x16x32_f16 v[86:89], v[164:167], v[216:219], v[86:89]
	v_mfma_f32_16x16x32_f16 v[78:81], v[168:171], v[216:219], v[78:81]
	v_mfma_f32_16x16x32_f16 v[66:69], v[164:167], v[220:223], v[66:69]
	v_mfma_f32_16x16x32_f16 v[58:61], v[168:171], v[220:223], v[58:61]
	v_mfma_f32_16x16x32_f16 v[118:121], v[172:175], v[208:211], v[118:121]
	v_mfma_f32_16x16x32_f16 v[110:113], v[176:179], v[208:211], v[110:113]
	v_mfma_f32_16x16x32_f16 v[102:105], v[172:175], v[212:215], v[102:105]
	v_mfma_f32_16x16x32_f16 v[94:97], v[176:179], v[212:215], v[94:97]
	v_mfma_f32_16x16x32_f16 v[86:89], v[172:175], v[224:227], v[86:89]
	v_mfma_f32_16x16x32_f16 v[78:81], v[176:179], v[224:227], v[78:81]
	v_mfma_f32_16x16x32_f16 v[66:69], v[172:175], v[228:231], v[66:69]
	v_mfma_f32_16x16x32_f16 v[58:61], v[176:179], v[228:231], v[58:61]
	v_mfma_f32_16x16x32_f16 v[126:129], v[180:183], v[196:199], v[126:129]
	v_mfma_f32_16x16x32_f16 v[122:125], v[184:187], v[196:199], v[122:125]
	v_mfma_f32_16x16x32_f16 v[114:117], v[180:183], v[204:207], v[114:117]
	v_mfma_f32_16x16x32_f16 v[106:109], v[184:187], v[204:207], v[106:109]
	v_mfma_f32_16x16x32_f16 v[98:101], v[180:183], v[216:219], v[98:101]
	v_mfma_f32_16x16x32_f16 v[90:93], v[184:187], v[216:219], v[90:93]
	v_mfma_f32_16x16x32_f16 v[82:85], v[180:183], v[220:223], v[82:85]
	v_mfma_f32_16x16x32_f16 v[74:77], v[184:187], v[220:223], v[74:77]
	v_mfma_f32_16x16x32_f16 v[126:129], v[188:191], v[208:211], v[126:129]
	v_mfma_f32_16x16x32_f16 v[122:125], v[192:195], v[208:211], v[122:125]
	v_mfma_f32_16x16x32_f16 v[114:117], v[188:191], v[212:215], v[114:117]
	v_mfma_f32_16x16x32_f16 v[106:109], v[192:195], v[212:215], v[106:109]
	v_mfma_f32_16x16x32_f16 v[98:101], v[188:191], v[224:227], v[98:101]
	v_mfma_f32_16x16x32_f16 v[90:93], v[192:195], v[224:227], v[90:93]
	v_mfma_f32_16x16x32_f16 v[82:85], v[188:191], v[228:231], v[82:85]
	v_mfma_f32_16x16x32_f16 v[74:77], v[192:195], v[228:231], v[74:77]
	s_barrier
	s_mov_b32 m0, s26
	s_mov_b32 s10, s50
	s_mov_b32 s11, s51
	ds_read_b128 v[196:199], v161 offset:16384
	ds_read_b128 v[204:207], v161 offset:18432
	ds_read_b128 v[208:211], v162 offset:16384
	ds_read_b128 v[212:215], v162 offset:18432
	ds_read_b128 v[216:219], v161 offset:20480
	ds_read_b128 v[220:223], v161 offset:22528
	ds_read_b128 v[224:227], v162 offset:20480
	ds_read_b128 v[228:231], v162 offset:22528
	buffer_load_dwordx4 v154, s[8:11], s62 offen lds
	s_mov_b32 m0, s27
	s_add_i32 s81, s62, 0x80000
	buffer_load_dwordx4 v156, s[8:11], s62 offen lds
	s_mov_b32 m0, s28
	s_nop 0
	buffer_load_dwordx4 v154, s[8:11], s81 offen lds
	s_mov_b32 m0, s29
	s_nop 0
	buffer_load_dwordx4 v156, s[8:11], s81 offen lds
	s_mov_b32 m0, s3
	s_nop 0
	buffer_load_dwordx4 v153, s[48:51], s78 offen lds
	s_mov_b32 m0, s30
	s_nop 0
	buffer_load_dwordx4 v155, s[48:51], s78 offen lds
	s_waitcnt vmcnt(8)
	s_waitcnt lgkmcnt(0)
	s_barrier
	s_waitcnt lgkmcnt(0)
	v_mfma_f32_16x16x32_f16 v[54:57], v[164:167], v[196:199], v[54:57]
	v_mfma_f32_16x16x32_f16 v[46:49], v[168:171], v[196:199], v[46:49]
	v_mfma_f32_16x16x32_f16 v[38:41], v[164:167], v[204:207], v[38:41]
	v_mfma_f32_16x16x32_f16 v[30:33], v[168:171], v[204:207], v[30:33]
	v_mfma_f32_16x16x32_f16 v[22:25], v[164:167], v[216:219], v[22:25]
	v_mfma_f32_16x16x32_f16 v[14:17], v[168:171], v[216:219], v[14:17]
	v_mfma_f32_16x16x32_f16 v[6:9], v[164:167], v[220:223], v[6:9]
	v_mfma_f32_16x16x32_f16 v[2:5], v[168:171], v[220:223], v[2:5]
	v_mfma_f32_16x16x32_f16 v[54:57], v[172:175], v[208:211], v[54:57]
	v_mfma_f32_16x16x32_f16 v[46:49], v[176:179], v[208:211], v[46:49]
	v_mfma_f32_16x16x32_f16 v[38:41], v[172:175], v[212:215], v[38:41]
	v_mfma_f32_16x16x32_f16 v[30:33], v[176:179], v[212:215], v[30:33]
	v_mfma_f32_16x16x32_f16 v[22:25], v[172:175], v[224:227], v[22:25]
	v_mfma_f32_16x16x32_f16 v[14:17], v[176:179], v[224:227], v[14:17]
	v_mfma_f32_16x16x32_f16 v[6:9], v[172:175], v[228:231], v[6:9]
	v_mfma_f32_16x16x32_f16 v[2:5], v[176:179], v[228:231], v[2:5]
	v_mfma_f32_16x16x32_f16 v[70:73], v[180:183], v[196:199], v[70:73]
	v_mfma_f32_16x16x32_f16 v[62:65], v[184:187], v[196:199], v[62:65]
	v_mfma_f32_16x16x32_f16 v[50:53], v[180:183], v[204:207], v[50:53]
	v_mfma_f32_16x16x32_f16 v[42:45], v[184:187], v[204:207], v[42:45]
	v_mfma_f32_16x16x32_f16 v[34:37], v[180:183], v[216:219], v[34:37]
	v_mfma_f32_16x16x32_f16 v[26:29], v[184:187], v[216:219], v[26:29]
	v_mfma_f32_16x16x32_f16 v[18:21], v[180:183], v[220:223], v[18:21]
	v_mfma_f32_16x16x32_f16 v[10:13], v[184:187], v[220:223], v[10:13]
	v_mfma_f32_16x16x32_f16 v[70:73], v[188:191], v[208:211], v[70:73]
	v_mfma_f32_16x16x32_f16 v[62:65], v[192:195], v[208:211], v[62:65]
	v_mfma_f32_16x16x32_f16 v[50:53], v[188:191], v[212:215], v[50:53]
	v_mfma_f32_16x16x32_f16 v[42:45], v[192:195], v[212:215], v[42:45]
	v_mfma_f32_16x16x32_f16 v[34:37], v[188:191], v[224:227], v[34:37]
	v_mfma_f32_16x16x32_f16 v[26:29], v[192:195], v[224:227], v[26:29]
	v_mfma_f32_16x16x32_f16 v[18:21], v[188:191], v[228:231], v[18:21]
	v_mfma_f32_16x16x32_f16 v[10:13], v[192:195], v[228:231], v[10:13]
	s_barrier
	s_add_i32 s81, 0, 0x18000
	v_add_u32_e32 v0, s81, v157
	v_add_u32_e32 v147, s81, v158
	s_add_i32 s81, 0, 0x1c000
	ds_read_b128 v[164:167], v0
	ds_read_b128 v[168:171], v0 offset:2048
	ds_read_b128 v[172:175], v147
	ds_read_b128 v[176:179], v147 offset:2048
	v_add_u32_e32 v0, s81, v157
	v_add_u32_e32 v147, s81, v158
	ds_read_b128 v[180:183], v0
	ds_read_b128 v[184:187], v0 offset:2048
	ds_read_b128 v[188:191], v147
	ds_read_b128 v[192:195], v147 offset:2048
	s_add_i32 s78, s78, 0x80000
	s_mov_b32 m0, s31
	ds_read_b128 v[196:199], v161 offset:32768
	ds_read_b128 v[204:207], v161 offset:34816
	ds_read_b128 v[208:211], v162 offset:32768
	ds_read_b128 v[212:215], v162 offset:34816
	ds_read_b128 v[216:219], v161 offset:36864
	ds_read_b128 v[220:223], v161 offset:38912
	ds_read_b128 v[224:227], v162 offset:36864
	ds_read_b128 v[228:231], v162 offset:38912
	buffer_load_dwordx4 v153, s[48:51], s78 offen lds
	s_mov_b32 m0, s34
	s_nop 0
	buffer_load_dwordx4 v155, s[48:51], s78 offen lds
	s_waitcnt vmcnt(8)
	s_waitcnt lgkmcnt(0)
	s_barrier
	s_waitcnt lgkmcnt(0)
	v_mfma_f32_16x16x32_f16 v[118:121], v[164:167], v[196:199], v[118:121]
	v_mfma_f32_16x16x32_f16 v[110:113], v[168:171], v[196:199], v[110:113]
	v_mfma_f32_16x16x32_f16 v[102:105], v[164:167], v[204:207], v[102:105]
	v_mfma_f32_16x16x32_f16 v[94:97], v[168:171], v[204:207], v[94:97]
	v_mfma_f32_16x16x32_f16 v[86:89], v[164:167], v[216:219], v[86:89]
	v_mfma_f32_16x16x32_f16 v[78:81], v[168:171], v[216:219], v[78:81]
	v_mfma_f32_16x16x32_f16 v[66:69], v[164:167], v[220:223], v[66:69]
	v_mfma_f32_16x16x32_f16 v[58:61], v[168:171], v[220:223], v[58:61]
	v_mfma_f32_16x16x32_f16 v[118:121], v[172:175], v[208:211], v[118:121]
	v_mfma_f32_16x16x32_f16 v[110:113], v[176:179], v[208:211], v[110:113]
	v_mfma_f32_16x16x32_f16 v[102:105], v[172:175], v[212:215], v[102:105]
	v_mfma_f32_16x16x32_f16 v[94:97], v[176:179], v[212:215], v[94:97]
	v_mfma_f32_16x16x32_f16 v[86:89], v[172:175], v[224:227], v[86:89]
	v_mfma_f32_16x16x32_f16 v[78:81], v[176:179], v[224:227], v[78:81]
	v_mfma_f32_16x16x32_f16 v[66:69], v[172:175], v[228:231], v[66:69]
	v_mfma_f32_16x16x32_f16 v[58:61], v[176:179], v[228:231], v[58:61]
	v_mfma_f32_16x16x32_f16 v[126:129], v[180:183], v[196:199], v[126:129]
	v_mfma_f32_16x16x32_f16 v[122:125], v[184:187], v[196:199], v[122:125]
	v_mfma_f32_16x16x32_f16 v[114:117], v[180:183], v[204:207], v[114:117]
	v_mfma_f32_16x16x32_f16 v[106:109], v[184:187], v[204:207], v[106:109]
	v_mfma_f32_16x16x32_f16 v[98:101], v[180:183], v[216:219], v[98:101]
	v_mfma_f32_16x16x32_f16 v[90:93], v[184:187], v[216:219], v[90:93]
	v_mfma_f32_16x16x32_f16 v[82:85], v[180:183], v[220:223], v[82:85]
	v_mfma_f32_16x16x32_f16 v[74:77], v[184:187], v[220:223], v[74:77]
	v_mfma_f32_16x16x32_f16 v[126:129], v[188:191], v[208:211], v[126:129]
	v_mfma_f32_16x16x32_f16 v[122:125], v[192:195], v[208:211], v[122:125]
	v_mfma_f32_16x16x32_f16 v[114:117], v[188:191], v[212:215], v[114:117]
	v_mfma_f32_16x16x32_f16 v[106:109], v[192:195], v[212:215], v[106:109]
	v_mfma_f32_16x16x32_f16 v[98:101], v[188:191], v[224:227], v[98:101]
	v_mfma_f32_16x16x32_f16 v[90:93], v[192:195], v[224:227], v[90:93]
	v_mfma_f32_16x16x32_f16 v[82:85], v[188:191], v[228:231], v[82:85]
	v_mfma_f32_16x16x32_f16 v[74:77], v[192:195], v[228:231], v[74:77]
	s_barrier
	s_mov_b32 m0, s35
	ds_read_b128 v[196:199], v161 offset:49152
	ds_read_b128 v[204:207], v161 offset:51200
	ds_read_b128 v[208:211], v162 offset:49152
	ds_read_b128 v[212:215], v162 offset:51200
	ds_read_b128 v[216:219], v161 offset:53248
	ds_read_b128 v[220:223], v161 offset:55296
	ds_read_b128 v[224:227], v162 offset:53248
	ds_read_b128 v[228:231], v162 offset:55296
	buffer_load_dwordx4 v154, s[8:11], s65 offen lds
	s_mov_b32 m0, s36
	s_add_i32 s62, s62, 0x80080
	buffer_load_dwordx4 v156, s[8:11], s65 offen lds
	s_mov_b32 m0, s39
	s_nop 0
	buffer_load_dwordx4 v154, s[8:11], s62 offen lds
	s_mov_b32 m0, s40
	s_nop 0
	buffer_load_dwordx4 v156, s[8:11], s62 offen lds
	s_mov_b32 m0, s37
	s_nop 0
	buffer_load_dwordx4 v153, s[48:51], s64 offen lds
	s_mov_b32 m0, s38
	s_nop 0
	buffer_load_dwordx4 v155, s[48:51], s64 offen lds
	s_waitcnt vmcnt(8)
	s_waitcnt lgkmcnt(0)
	s_barrier
	s_waitcnt lgkmcnt(0)
	v_mfma_f32_16x16x32_f16 v[54:57], v[164:167], v[196:199], v[54:57]
	v_mfma_f32_16x16x32_f16 v[46:49], v[168:171], v[196:199], v[46:49]
	v_mfma_f32_16x16x32_f16 v[38:41], v[164:167], v[204:207], v[38:41]
	v_mfma_f32_16x16x32_f16 v[30:33], v[168:171], v[204:207], v[30:33]
	v_mfma_f32_16x16x32_f16 v[22:25], v[164:167], v[216:219], v[22:25]
	v_mfma_f32_16x16x32_f16 v[14:17], v[168:171], v[216:219], v[14:17]
	v_mfma_f32_16x16x32_f16 v[6:9], v[164:167], v[220:223], v[6:9]
	v_mfma_f32_16x16x32_f16 v[2:5], v[168:171], v[220:223], v[2:5]
	v_mfma_f32_16x16x32_f16 v[54:57], v[172:175], v[208:211], v[54:57]
	v_mfma_f32_16x16x32_f16 v[46:49], v[176:179], v[208:211], v[46:49]
	v_mfma_f32_16x16x32_f16 v[38:41], v[172:175], v[212:215], v[38:41]
	v_mfma_f32_16x16x32_f16 v[30:33], v[176:179], v[212:215], v[30:33]
	v_mfma_f32_16x16x32_f16 v[22:25], v[172:175], v[224:227], v[22:25]
	v_mfma_f32_16x16x32_f16 v[14:17], v[176:179], v[224:227], v[14:17]
	v_mfma_f32_16x16x32_f16 v[6:9], v[172:175], v[228:231], v[6:9]
	v_mfma_f32_16x16x32_f16 v[2:5], v[176:179], v[228:231], v[2:5]
	v_mfma_f32_16x16x32_f16 v[70:73], v[180:183], v[196:199], v[70:73]
	v_mfma_f32_16x16x32_f16 v[62:65], v[184:187], v[196:199], v[62:65]
	v_mfma_f32_16x16x32_f16 v[50:53], v[180:183], v[204:207], v[50:53]
	v_mfma_f32_16x16x32_f16 v[42:45], v[184:187], v[204:207], v[42:45]
	v_mfma_f32_16x16x32_f16 v[34:37], v[180:183], v[216:219], v[34:37]
	v_mfma_f32_16x16x32_f16 v[26:29], v[184:187], v[216:219], v[26:29]
	v_mfma_f32_16x16x32_f16 v[18:21], v[180:183], v[220:223], v[18:21]
	v_mfma_f32_16x16x32_f16 v[10:13], v[184:187], v[220:223], v[10:13]
	v_mfma_f32_16x16x32_f16 v[70:73], v[188:191], v[208:211], v[70:73]
	v_mfma_f32_16x16x32_f16 v[62:65], v[192:195], v[208:211], v[62:65]
	v_mfma_f32_16x16x32_f16 v[50:53], v[188:191], v[212:215], v[50:53]
	v_mfma_f32_16x16x32_f16 v[42:45], v[192:195], v[212:215], v[42:45]
	v_mfma_f32_16x16x32_f16 v[34:37], v[188:191], v[224:227], v[34:37]
	v_mfma_f32_16x16x32_f16 v[26:29], v[192:195], v[224:227], v[26:29]
	v_mfma_f32_16x16x32_f16 v[18:21], v[188:191], v[228:231], v[18:21]
	v_mfma_f32_16x16x32_f16 v[10:13], v[192:195], v[228:231], v[10:13]
	s_barrier

.Lc0b_first:
	s_add_i32 s55, s52, 0xfff80080
	s_and_b64 s[10:11], s[10:11], exec
	s_cselect_b32 s60, s46, s55
	s_cselect_b32 s55, s47, s53
	s_add_i32 s10, 0, 0x10000
	v_add_u32_e32 v0, s10, v157
	v_add_u32_e32 v147, s10, v158
	s_add_i32 s10, 0, 0x14000
	ds_read_b128 v[164:167], v0
	ds_read_b128 v[168:171], v0 offset:2048
	ds_read_b128 v[172:175], v147
	ds_read_b128 v[176:179], v147 offset:2048
	v_add_u32_e32 v0, s10, v157
	v_add_u32_e32 v147, s10, v158
	ds_read_b128 v[180:183], v0
	ds_read_b128 v[184:187], v0 offset:2048
	ds_read_b128 v[188:191], v147
	ds_read_b128 v[192:195], v147 offset:2048
	s_or_b32 s56, s60, 0x80
	s_or_b32 s58, s55, 0x80
	s_mov_b32 m0, s37
	ds_read_b128 v[196:199], v161
	ds_read_b128 v[204:207], v161 offset:2048
	ds_read_b128 v[208:211], v162
	ds_read_b128 v[212:215], v162 offset:2048
	ds_read_b128 v[216:219], v161 offset:4096
	ds_read_b128 v[220:223], v161 offset:6144
	ds_read_b128 v[224:227], v162 offset:4096
	ds_read_b128 v[228:231], v162 offset:6144
	buffer_load_dwordx4 v151, s[48:51], s52 offen lds
	s_mov_b32 m0, s38
	s_nop 0
	buffer_load_dwordx4 v155, s[48:51], s52 offen lds
	s_waitcnt vmcnt(8)
	s_waitcnt lgkmcnt(0)
	s_barrier
	s_waitcnt lgkmcnt(0)
	v_mfma_f32_16x16x32_f16 v[94:97], v[164:167], v[196:199], 0
	v_mfma_f32_16x16x32_f16 v[98:101], v[168:171], v[196:199], 0
	v_mfma_f32_16x16x32_f16 v[62:65], v[164:167], v[204:207], 0
	v_mfma_f32_16x16x32_f16 v[74:77], v[168:171], v[204:207], 0
	v_mfma_f32_16x16x32_f16 v[34:37], v[164:167], v[216:219], 0
	v_mfma_f32_16x16x32_f16 v[42:45], v[168:171], v[216:219], 0
	v_mfma_f32_16x16x32_f16 v[14:17], v[164:167], v[220:223], 0
	v_mfma_f32_16x16x32_f16 v[22:25], v[168:171], v[220:223], 0
	v_mfma_f32_16x16x32_f16 v[94:97], v[172:175], v[208:211], v[94:97]
	v_mfma_f32_16x16x32_f16 v[98:101], v[176:179], v[208:211], v[98:101]
	v_mfma_f32_16x16x32_f16 v[62:65], v[172:175], v[212:215], v[62:65]
	v_mfma_f32_16x16x32_f16 v[74:77], v[176:179], v[212:215], v[74:77]
	v_mfma_f32_16x16x32_f16 v[34:37], v[172:175], v[224:227], v[34:37]
	v_mfma_f32_16x16x32_f16 v[42:45], v[176:179], v[224:227], v[42:45]
	v_mfma_f32_16x16x32_f16 v[14:17], v[172:175], v[228:231], v[14:17]
	v_mfma_f32_16x16x32_f16 v[22:25], v[176:179], v[228:231], v[22:25]
	v_mfma_f32_16x16x32_f16 v[122:125], v[180:183], v[196:199], 0
	v_mfma_f32_16x16x32_f16 v[126:129], v[184:187], v[196:199], 0
	v_mfma_f32_16x16x32_f16 v[110:113], v[180:183], v[204:207], 0
	v_mfma_f32_16x16x32_f16 v[118:121], v[184:187], v[204:207], 0
	v_mfma_f32_16x16x32_f16 v[86:89], v[180:183], v[216:219], 0
	v_mfma_f32_16x16x32_f16 v[102:105], v[184:187], v[216:219], 0
	v_mfma_f32_16x16x32_f16 v[70:73], v[180:183], v[220:223], 0
	v_mfma_f32_16x16x32_f16 v[78:81], v[184:187], v[220:223], 0
	v_mfma_f32_16x16x32_f16 v[122:125], v[188:191], v[208:211], v[122:125]
	v_mfma_f32_16x16x32_f16 v[126:129], v[192:195], v[208:211], v[126:129]
	v_mfma_f32_16x16x32_f16 v[110:113], v[188:191], v[212:215], v[110:113]
	v_mfma_f32_16x16x32_f16 v[118:121], v[192:195], v[212:215], v[118:121]
	v_mfma_f32_16x16x32_f16 v[86:89], v[188:191], v[224:227], v[86:89]
	v_mfma_f32_16x16x32_f16 v[102:105], v[192:195], v[224:227], v[102:105]
	v_mfma_f32_16x16x32_f16 v[70:73], v[188:191], v[228:231], v[70:73]
	v_mfma_f32_16x16x32_f16 v[78:81], v[192:195], v[228:231], v[78:81]
	s_barrier
	s_mov_b32 m0, s2
	s_mov_b32 s10, s50
	s_mov_b32 s11, s51
	ds_read_b128 v[196:199], v161 offset:16384
	ds_read_b128 v[204:207], v161 offset:18432
	ds_read_b128 v[208:211], v162 offset:16384
	ds_read_b128 v[212:215], v162 offset:18432
	ds_read_b128 v[216:219], v161 offset:20480
	ds_read_b128 v[220:223], v161 offset:22528
	ds_read_b128 v[224:227], v162 offset:20480
	ds_read_b128 v[228:231], v162 offset:22528
	buffer_load_dwordx4 v153, s[8:11], s55 offen lds
	s_mov_b32 m0, s3
	s_add_i32 s61, s55, 0x80000
	buffer_load_dwordx4 v156, s[8:11], s55 offen lds
	s_mov_b32 m0, s20
	s_nop 0
	buffer_load_dwordx4 v153, s[8:11], s61 offen lds
	s_mov_b32 m0, s21
	s_nop 0
	buffer_load_dwordx4 v156, s[8:11], s61 offen lds
	s_mov_b32 m0, s1
	s_nop 0
	buffer_load_dwordx4 v151, s[48:51], s60 offen lds
	s_mov_b32 m0, s26
	s_nop 0
	buffer_load_dwordx4 v155, s[48:51], s60 offen lds
	s_waitcnt vmcnt(8)
	s_waitcnt lgkmcnt(0)
	s_barrier
	s_waitcnt lgkmcnt(0)
	v_mfma_f32_16x16x32_f16 v[54:57], v[164:167], v[196:199], 0
	v_mfma_f32_16x16x32_f16 v[66:69], v[168:171], v[196:199], 0
	v_mfma_f32_16x16x32_f16 v[30:33], v[164:167], v[204:207], 0
	v_mfma_f32_16x16x32_f16 v[38:41], v[168:171], v[204:207], 0
	v_mfma_f32_16x16x32_f16 v[10:13], v[164:167], v[216:219], 0
	v_mfma_f32_16x16x32_f16 v[18:21], v[168:171], v[216:219], 0
	v_mfma_f32_16x16x32_f16 v[2:5], v[164:167], v[220:223], 0
	v_mfma_f32_16x16x32_f16 v[6:9], v[168:171], v[220:223], 0
	v_mfma_f32_16x16x32_f16 v[54:57], v[172:175], v[208:211], v[54:57]
	v_mfma_f32_16x16x32_f16 v[66:69], v[176:179], v[208:211], v[66:69]
	v_mfma_f32_16x16x32_f16 v[30:33], v[172:175], v[212:215], v[30:33]
	v_mfma_f32_16x16x32_f16 v[38:41], v[176:179], v[212:215], v[38:41]
	v_mfma_f32_16x16x32_f16 v[10:13], v[172:175], v[224:227], v[10:13]
	v_mfma_f32_16x16x32_f16 v[18:21], v[176:179], v[224:227], v[18:21]
	v_mfma_f32_16x16x32_f16 v[2:5], v[172:175], v[228:231], v[2:5]
	v_mfma_f32_16x16x32_f16 v[6:9], v[176:179], v[228:231], v[6:9]
	v_mfma_f32_16x16x32_f16 v[106:109], v[180:183], v[196:199], 0
	v_mfma_f32_16x16x32_f16 v[114:117], v[184:187], v[196:199], 0
	v_mfma_f32_16x16x32_f16 v[82:85], v[180:183], v[204:207], 0
	v_mfma_f32_16x16x32_f16 v[90:93], v[184:187], v[204:207], 0
	v_mfma_f32_16x16x32_f16 v[46:49], v[180:183], v[216:219], 0
	v_mfma_f32_16x16x32_f16 v[58:61], v[184:187], v[216:219], 0
	v_mfma_f32_16x16x32_f16 v[26:29], v[180:183], v[220:223], 0
	v_mfma_f32_16x16x32_f16 v[50:53], v[184:187], v[220:223], 0
	v_mfma_f32_16x16x32_f16 v[106:109], v[188:191], v[208:211], v[106:109]
	v_mfma_f32_16x16x32_f16 v[114:117], v[192:195], v[208:211], v[114:117]
	v_mfma_f32_16x16x32_f16 v[82:85], v[188:191], v[212:215], v[82:85]
	v_mfma_f32_16x16x32_f16 v[90:93], v[192:195], v[212:215], v[90:93]
	v_mfma_f32_16x16x32_f16 v[46:49], v[188:191], v[224:227], v[46:49]
	v_mfma_f32_16x16x32_f16 v[58:61], v[192:195], v[224:227], v[58:61]
	v_mfma_f32_16x16x32_f16 v[26:29], v[188:191], v[228:231], v[26:29]
	v_mfma_f32_16x16x32_f16 v[50:53], v[192:195], v[228:231], v[50:53]
	s_barrier
	s_add_i32 s61, 0, 0x18000
	v_add_u32_e32 v0, s61, v157
	v_add_u32_e32 v147, s61, v158
	s_add_i32 s61, 0, 0x1c000
	ds_read_b128 v[164:167], v0
	ds_read_b128 v[168:171], v0 offset:2048
	ds_read_b128 v[172:175], v147
	ds_read_b128 v[176:179], v147 offset:2048
	v_add_u32_e32 v0, s61, v157
	v_add_u32_e32 v147, s61, v158
	ds_read_b128 v[180:183], v0
	ds_read_b128 v[184:187], v0 offset:2048
	ds_read_b128 v[188:191], v147
	ds_read_b128 v[192:195], v147 offset:2048
	s_add_i32 s60, s60, 0x80000
	s_mov_b32 m0, s27
	ds_read_b128 v[196:199], v161 offset:32768
	ds_read_b128 v[204:207], v161 offset:34816
	ds_read_b128 v[208:211], v162 offset:32768
	ds_read_b128 v[212:215], v162 offset:34816
	ds_read_b128 v[216:219], v161 offset:36864
	ds_read_b128 v[220:223], v161 offset:38912
	ds_read_b128 v[224:227], v162 offset:36864
	ds_read_b128 v[228:231], v162 offset:38912
	buffer_load_dwordx4 v151, s[48:51], s60 offen lds
	s_mov_b32 m0, s28
	s_nop 0
	buffer_load_dwordx4 v155, s[48:51], s60 offen lds
	s_waitcnt vmcnt(8)
	s_waitcnt lgkmcnt(0)
	s_barrier
	s_waitcnt lgkmcnt(0)
	v_mfma_f32_16x16x32_f16 v[94:97], v[164:167], v[196:199], v[94:97]
	v_mfma_f32_16x16x32_f16 v[98:101], v[168:171], v[196:199], v[98:101]
	v_mfma_f32_16x16x32_f16 v[62:65], v[164:167], v[204:207], v[62:65]
	v_mfma_f32_16x16x32_f16 v[74:77], v[168:171], v[204:207], v[74:77]
	v_mfma_f32_16x16x32_f16 v[34:37], v[164:167], v[216:219], v[34:37]
	v_mfma_f32_16x16x32_f16 v[42:45], v[168:171], v[216:219], v[42:45]
	v_mfma_f32_16x16x32_f16 v[14:17], v[164:167], v[220:223], v[14:17]
	v_mfma_f32_16x16x32_f16 v[22:25], v[168:171], v[220:223], v[22:25]
	v_mfma_f32_16x16x32_f16 v[94:97], v[172:175], v[208:211], v[94:97]
	v_mfma_f32_16x16x32_f16 v[98:101], v[176:179], v[208:211], v[98:101]
	v_mfma_f32_16x16x32_f16 v[62:65], v[172:175], v[212:215], v[62:65]
	v_mfma_f32_16x16x32_f16 v[74:77], v[176:179], v[212:215], v[74:77]
	v_mfma_f32_16x16x32_f16 v[34:37], v[172:175], v[224:227], v[34:37]
	v_mfma_f32_16x16x32_f16 v[42:45], v[176:179], v[224:227], v[42:45]
	v_mfma_f32_16x16x32_f16 v[14:17], v[172:175], v[228:231], v[14:17]
	v_mfma_f32_16x16x32_f16 v[22:25], v[176:179], v[228:231], v[22:25]
	v_mfma_f32_16x16x32_f16 v[122:125], v[180:183], v[196:199], v[122:125]
	v_mfma_f32_16x16x32_f16 v[126:129], v[184:187], v[196:199], v[126:129]
	v_mfma_f32_16x16x32_f16 v[110:113], v[180:183], v[204:207], v[110:113]
	v_mfma_f32_16x16x32_f16 v[118:121], v[184:187], v[204:207], v[118:121]
	v_mfma_f32_16x16x32_f16 v[86:89], v[180:183], v[216:219], v[86:89]
	v_mfma_f32_16x16x32_f16 v[102:105], v[184:187], v[216:219], v[102:105]
	v_mfma_f32_16x16x32_f16 v[70:73], v[180:183], v[220:223], v[70:73]
	v_mfma_f32_16x16x32_f16 v[78:81], v[184:187], v[220:223], v[78:81]
	v_mfma_f32_16x16x32_f16 v[122:125], v[188:191], v[208:211], v[122:125]
	v_mfma_f32_16x16x32_f16 v[126:129], v[192:195], v[208:211], v[126:129]
	v_mfma_f32_16x16x32_f16 v[110:113], v[188:191], v[212:215], v[110:113]
	v_mfma_f32_16x16x32_f16 v[118:121], v[192:195], v[212:215], v[118:121]
	v_mfma_f32_16x16x32_f16 v[86:89], v[188:191], v[224:227], v[86:89]
	v_mfma_f32_16x16x32_f16 v[102:105], v[192:195], v[224:227], v[102:105]
	v_mfma_f32_16x16x32_f16 v[70:73], v[188:191], v[228:231], v[70:73]
	v_mfma_f32_16x16x32_f16 v[78:81], v[192:195], v[228:231], v[78:81]
	s_barrier
	s_mov_b32 m0, s29
	ds_read_b128 v[196:199], v161 offset:49152
	ds_read_b128 v[204:207], v161 offset:51200
	ds_read_b128 v[208:211], v162 offset:49152
	ds_read_b128 v[212:215], v162 offset:51200
	ds_read_b128 v[216:219], v161 offset:53248
	ds_read_b128 v[220:223], v161 offset:55296
	ds_read_b128 v[224:227], v162 offset:53248
	ds_read_b128 v[228:231], v162 offset:55296
	buffer_load_dwordx4 v153, s[8:11], s58 offen lds
	s_mov_b32 m0, s30
	s_add_i32 s55, s55, 0x80080
	buffer_load_dwordx4 v156, s[8:11], s58 offen lds
	s_mov_b32 m0, s35
	s_nop 0
	buffer_load_dwordx4 v153, s[8:11], s55 offen lds
	s_mov_b32 m0, s36
	s_nop 0
	buffer_load_dwordx4 v156, s[8:11], s55 offen lds
	s_mov_b32 m0, s31
	s_nop 0
	buffer_load_dwordx4 v151, s[48:51], s56 offen lds
	s_mov_b32 m0, s34
	s_nop 0
	buffer_load_dwordx4 v155, s[48:51], s56 offen lds
	s_waitcnt vmcnt(8)
	s_waitcnt lgkmcnt(0)
	s_barrier
	s_waitcnt lgkmcnt(0)
	v_mfma_f32_16x16x32_f16 v[54:57], v[164:167], v[196:199], v[54:57]
	v_mfma_f32_16x16x32_f16 v[66:69], v[168:171], v[196:199], v[66:69]
	v_mfma_f32_16x16x32_f16 v[30:33], v[164:167], v[204:207], v[30:33]
	v_mfma_f32_16x16x32_f16 v[38:41], v[168:171], v[204:207], v[38:41]
	v_mfma_f32_16x16x32_f16 v[10:13], v[164:167], v[216:219], v[10:13]
	v_mfma_f32_16x16x32_f16 v[18:21], v[168:171], v[216:219], v[18:21]
	v_mfma_f32_16x16x32_f16 v[2:5], v[164:167], v[220:223], v[2:5]
	v_mfma_f32_16x16x32_f16 v[6:9], v[168:171], v[220:223], v[6:9]
	v_mfma_f32_16x16x32_f16 v[54:57], v[172:175], v[208:211], v[54:57]
	v_mfma_f32_16x16x32_f16 v[66:69], v[176:179], v[208:211], v[66:69]
	v_mfma_f32_16x16x32_f16 v[30:33], v[172:175], v[212:215], v[30:33]
	v_mfma_f32_16x16x32_f16 v[38:41], v[176:179], v[212:215], v[38:41]
	v_mfma_f32_16x16x32_f16 v[10:13], v[172:175], v[224:227], v[10:13]
	v_mfma_f32_16x16x32_f16 v[18:21], v[176:179], v[224:227], v[18:21]
	v_mfma_f32_16x16x32_f16 v[2:5], v[172:175], v[228:231], v[2:5]
	v_mfma_f32_16x16x32_f16 v[6:9], v[176:179], v[228:231], v[6:9]
	v_mfma_f32_16x16x32_f16 v[106:109], v[180:183], v[196:199], v[106:109]
	v_mfma_f32_16x16x32_f16 v[114:117], v[184:187], v[196:199], v[114:117]
	v_mfma_f32_16x16x32_f16 v[82:85], v[180:183], v[204:207], v[82:85]
	v_mfma_f32_16x16x32_f16 v[90:93], v[184:187], v[204:207], v[90:93]
	v_mfma_f32_16x16x32_f16 v[46:49], v[180:183], v[216:219], v[46:49]
	v_mfma_f32_16x16x32_f16 v[58:61], v[184:187], v[216:219], v[58:61]
	v_mfma_f32_16x16x32_f16 v[26:29], v[180:183], v[220:223], v[26:29]
	v_mfma_f32_16x16x32_f16 v[50:53], v[184:187], v[220:223], v[50:53]
	v_mfma_f32_16x16x32_f16 v[106:109], v[188:191], v[208:211], v[106:109]
	v_mfma_f32_16x16x32_f16 v[114:117], v[192:195], v[208:211], v[114:117]
	v_mfma_f32_16x16x32_f16 v[82:85], v[188:191], v[212:215], v[82:85]
	v_mfma_f32_16x16x32_f16 v[90:93], v[192:195], v[212:215], v[90:93]
	v_mfma_f32_16x16x32_f16 v[46:49], v[188:191], v[224:227], v[46:49]
	v_mfma_f32_16x16x32_f16 v[58:61], v[192:195], v[224:227], v[58:61]
	v_mfma_f32_16x16x32_f16 v[26:29], v[188:191], v[228:231], v[26:29]
	v_mfma_f32_16x16x32_f16 v[50:53], v[192:195], v[228:231], v[50:53]
	s_barrier
	s_branch .Lc0b_tail
.Lc0b_final:
	s_add_i32 s55, s52, 0xfff80080
	s_and_b64 s[10:11], s[10:11], exec
	s_cselect_b32 s60, s46, s55
	s_cselect_b32 s55, s47, s53
	s_add_i32 s10, 0, 0x10000
	v_add_u32_e32 v0, s10, v157
	v_add_u32_e32 v147, s10, v158
	s_add_i32 s10, 0, 0x14000
	ds_read_b128 v[164:167], v0
	ds_read_b128 v[168:171], v0 offset:2048
	ds_read_b128 v[172:175], v147
	ds_read_b128 v[176:179], v147 offset:2048
	v_add_u32_e32 v0, s10, v157
	v_add_u32_e32 v147, s10, v158
	ds_read_b128 v[180:183], v0
	ds_read_b128 v[184:187], v0 offset:2048
	ds_read_b128 v[188:191], v147
	ds_read_b128 v[192:195], v147 offset:2048
	s_or_b32 s56, s60, 0x80
	s_or_b32 s58, s55, 0x80
	s_mov_b32 m0, s37
	ds_read_b128 v[196:199], v161
	ds_read_b128 v[204:207], v161 offset:2048
	ds_read_b128 v[208:211], v162
	ds_read_b128 v[212:215], v162 offset:2048
	ds_read_b128 v[216:219], v161 offset:4096
	ds_read_b128 v[220:223], v161 offset:6144
	ds_read_b128 v[224:227], v162 offset:4096
	ds_read_b128 v[228:231], v162 offset:6144
	buffer_load_dwordx4 v151, s[48:51], s52 offen lds
	s_mov_b32 m0, s38
	s_nop 0
	buffer_load_dwordx4 v155, s[48:51], s52 offen lds
	s_waitcnt vmcnt(8)
	s_waitcnt lgkmcnt(0)
	s_barrier
	s_waitcnt lgkmcnt(0)
	v_mfma_f32_16x16x32_f16 v[94:97], v[164:167], v[196:199], v[94:97]
	v_mfma_f32_16x16x32_f16 v[98:101], v[168:171], v[196:199], v[98:101]
	v_mfma_f32_16x16x32_f16 v[62:65], v[164:167], v[204:207], v[62:65]
	v_mfma_f32_16x16x32_f16 v[74:77], v[168:171], v[204:207], v[74:77]
	v_mfma_f32_16x16x32_f16 v[34:37], v[164:167], v[216:219], v[34:37]
	v_mfma_f32_16x16x32_f16 v[42:45], v[168:171], v[216:219], v[42:45]
	v_mfma_f32_16x16x32_f16 v[14:17], v[164:167], v[220:223], v[14:17]
	v_mfma_f32_16x16x32_f16 v[22:25], v[168:171], v[220:223], v[22:25]
	v_mfma_f32_16x16x32_f16 v[94:97], v[172:175], v[208:211], v[94:97]
	v_mfma_f32_16x16x32_f16 v[98:101], v[176:179], v[208:211], v[98:101]
	v_mfma_f32_16x16x32_f16 v[62:65], v[172:175], v[212:215], v[62:65]
	v_mfma_f32_16x16x32_f16 v[74:77], v[176:179], v[212:215], v[74:77]
	v_mfma_f32_16x16x32_f16 v[34:37], v[172:175], v[224:227], v[34:37]
	v_mfma_f32_16x16x32_f16 v[42:45], v[176:179], v[224:227], v[42:45]
	v_mfma_f32_16x16x32_f16 v[14:17], v[172:175], v[228:231], v[14:17]
	v_mfma_f32_16x16x32_f16 v[22:25], v[176:179], v[228:231], v[22:25]
	v_mfma_f32_16x16x32_f16 v[122:125], v[180:183], v[196:199], v[122:125]
	v_mfma_f32_16x16x32_f16 v[126:129], v[184:187], v[196:199], v[126:129]
	v_mfma_f32_16x16x32_f16 v[110:113], v[180:183], v[204:207], v[110:113]
	v_mfma_f32_16x16x32_f16 v[118:121], v[184:187], v[204:207], v[118:121]
	v_mfma_f32_16x16x32_f16 v[86:89], v[180:183], v[216:219], v[86:89]
	v_mfma_f32_16x16x32_f16 v[102:105], v[184:187], v[216:219], v[102:105]
	v_mfma_f32_16x16x32_f16 v[70:73], v[180:183], v[220:223], v[70:73]
	v_mfma_f32_16x16x32_f16 v[78:81], v[184:187], v[220:223], v[78:81]
	v_mfma_f32_16x16x32_f16 v[122:125], v[188:191], v[208:211], v[122:125]
	v_mfma_f32_16x16x32_f16 v[126:129], v[192:195], v[208:211], v[126:129]
	v_mfma_f32_16x16x32_f16 v[110:113], v[188:191], v[212:215], v[110:113]
	v_mfma_f32_16x16x32_f16 v[118:121], v[192:195], v[212:215], v[118:121]
	v_mfma_f32_16x16x32_f16 v[86:89], v[188:191], v[224:227], v[86:89]
	v_mfma_f32_16x16x32_f16 v[102:105], v[192:195], v[224:227], v[102:105]
	v_mfma_f32_16x16x32_f16 v[70:73], v[188:191], v[228:231], v[70:73]
	v_mfma_f32_16x16x32_f16 v[78:81], v[192:195], v[228:231], v[78:81]
	s_barrier
	s_mov_b32 s10, s50
	s_mov_b32 s11, s51
	ds_read_b128 v[196:199], v161 offset:16384
	ds_read_b128 v[204:207], v161 offset:18432
	ds_read_b128 v[208:211], v162 offset:16384
	ds_read_b128 v[212:215], v162 offset:18432
	ds_read_b128 v[216:219], v161 offset:20480
	ds_read_b128 v[220:223], v161 offset:22528
	ds_read_b128 v[224:227], v162 offset:20480
	ds_read_b128 v[228:231], v162 offset:22528
	s_add_i32 s61, s55, 0x80000
	s_waitcnt vmcnt(2)
	s_waitcnt lgkmcnt(0)
	s_barrier
	s_waitcnt lgkmcnt(0)
	v_mfma_f32_16x16x32_f16 v[54:57], v[164:167], v[196:199], v[54:57]
	v_mfma_f32_16x16x32_f16 v[66:69], v[168:171], v[196:199], v[66:69]
	v_mfma_f32_16x16x32_f16 v[30:33], v[164:167], v[204:207], v[30:33]
	v_mfma_f32_16x16x32_f16 v[38:41], v[168:171], v[204:207], v[38:41]
	v_mfma_f32_16x16x32_f16 v[10:13], v[164:167], v[216:219], v[10:13]
	v_mfma_f32_16x16x32_f16 v[18:21], v[168:171], v[216:219], v[18:21]
	v_mfma_f32_16x16x32_f16 v[2:5], v[164:167], v[220:223], v[2:5]
	v_mfma_f32_16x16x32_f16 v[6:9], v[168:171], v[220:223], v[6:9]
	v_mfma_f32_16x16x32_f16 v[54:57], v[172:175], v[208:211], v[54:57]
	v_mfma_f32_16x16x32_f16 v[66:69], v[176:179], v[208:211], v[66:69]
	v_mfma_f32_16x16x32_f16 v[30:33], v[172:175], v[212:215], v[30:33]
	v_mfma_f32_16x16x32_f16 v[38:41], v[176:179], v[212:215], v[38:41]
	v_mfma_f32_16x16x32_f16 v[10:13], v[172:175], v[224:227], v[10:13]
	v_mfma_f32_16x16x32_f16 v[18:21], v[176:179], v[224:227], v[18:21]
	v_mfma_f32_16x16x32_f16 v[2:5], v[172:175], v[228:231], v[2:5]
	v_mfma_f32_16x16x32_f16 v[6:9], v[176:179], v[228:231], v[6:9]
	v_mfma_f32_16x16x32_f16 v[106:109], v[180:183], v[196:199], v[106:109]
	v_mfma_f32_16x16x32_f16 v[114:117], v[184:187], v[196:199], v[114:117]
	v_mfma_f32_16x16x32_f16 v[82:85], v[180:183], v[204:207], v[82:85]
	v_mfma_f32_16x16x32_f16 v[90:93], v[184:187], v[204:207], v[90:93]
	v_mfma_f32_16x16x32_f16 v[46:49], v[180:183], v[216:219], v[46:49]
	v_mfma_f32_16x16x32_f16 v[58:61], v[184:187], v[216:219], v[58:61]
	v_mfma_f32_16x16x32_f16 v[26:29], v[180:183], v[220:223], v[26:29]
	v_mfma_f32_16x16x32_f16 v[50:53], v[184:187], v[220:223], v[50:53]
	v_mfma_f32_16x16x32_f16 v[106:109], v[188:191], v[208:211], v[106:109]
	v_mfma_f32_16x16x32_f16 v[114:117], v[192:195], v[208:211], v[114:117]
	v_mfma_f32_16x16x32_f16 v[82:85], v[188:191], v[212:215], v[82:85]
	v_mfma_f32_16x16x32_f16 v[90:93], v[192:195], v[212:215], v[90:93]
	v_mfma_f32_16x16x32_f16 v[46:49], v[188:191], v[224:227], v[46:49]
	v_mfma_f32_16x16x32_f16 v[58:61], v[192:195], v[224:227], v[58:61]
	v_mfma_f32_16x16x32_f16 v[26:29], v[188:191], v[228:231], v[26:29]
	v_mfma_f32_16x16x32_f16 v[50:53], v[192:195], v[228:231], v[50:53]
	s_barrier
	s_add_i32 s61, 0, 0x18000
	v_add_u32_e32 v0, s61, v157
	v_add_u32_e32 v147, s61, v158
	s_add_i32 s61, 0, 0x1c000
	ds_read_b128 v[164:167], v0
	ds_read_b128 v[168:171], v0 offset:2048
	ds_read_b128 v[172:175], v147
	ds_read_b128 v[176:179], v147 offset:2048
	v_add_u32_e32 v0, s61, v157
	v_add_u32_e32 v147, s61, v158
	ds_read_b128 v[180:183], v0
	ds_read_b128 v[184:187], v0 offset:2048
	ds_read_b128 v[188:191], v147
	ds_read_b128 v[192:195], v147 offset:2048
	s_add_i32 s60, s60, 0x80000
	ds_read_b128 v[196:199], v161 offset:32768
	ds_read_b128 v[204:207], v161 offset:34816
	ds_read_b128 v[208:211], v162 offset:32768
	ds_read_b128 v[212:215], v162 offset:34816
	ds_read_b128 v[216:219], v161 offset:36864
	ds_read_b128 v[220:223], v161 offset:38912
	ds_read_b128 v[224:227], v162 offset:36864
	ds_read_b128 v[228:231], v162 offset:38912
	s_waitcnt vmcnt(0)
	s_waitcnt lgkmcnt(0)
	s_barrier
	s_waitcnt lgkmcnt(0)
	v_mfma_f32_16x16x32_f16 v[94:97], v[164:167], v[196:199], v[94:97]
	v_mfma_f32_16x16x32_f16 v[98:101], v[168:171], v[196:199], v[98:101]
	v_mfma_f32_16x16x32_f16 v[62:65], v[164:167], v[204:207], v[62:65]
	v_mfma_f32_16x16x32_f16 v[74:77], v[168:171], v[204:207], v[74:77]
	v_mfma_f32_16x16x32_f16 v[34:37], v[164:167], v[216:219], v[34:37]
	v_mfma_f32_16x16x32_f16 v[42:45], v[168:171], v[216:219], v[42:45]
	v_mfma_f32_16x16x32_f16 v[14:17], v[164:167], v[220:223], v[14:17]
	v_mfma_f32_16x16x32_f16 v[22:25], v[168:171], v[220:223], v[22:25]
	v_mfma_f32_16x16x32_f16 v[94:97], v[172:175], v[208:211], v[94:97]
	v_mfma_f32_16x16x32_f16 v[98:101], v[176:179], v[208:211], v[98:101]
	v_mfma_f32_16x16x32_f16 v[62:65], v[172:175], v[212:215], v[62:65]
	v_mfma_f32_16x16x32_f16 v[74:77], v[176:179], v[212:215], v[74:77]
	v_mfma_f32_16x16x32_f16 v[34:37], v[172:175], v[224:227], v[34:37]
	v_mfma_f32_16x16x32_f16 v[42:45], v[176:179], v[224:227], v[42:45]
	v_mfma_f32_16x16x32_f16 v[14:17], v[172:175], v[228:231], v[14:17]
	v_mfma_f32_16x16x32_f16 v[22:25], v[176:179], v[228:231], v[22:25]
	v_mfma_f32_16x16x32_f16 v[122:125], v[180:183], v[196:199], v[122:125]
	v_mfma_f32_16x16x32_f16 v[126:129], v[184:187], v[196:199], v[126:129]
	v_mfma_f32_16x16x32_f16 v[110:113], v[180:183], v[204:207], v[110:113]
	v_mfma_f32_16x16x32_f16 v[118:121], v[184:187], v[204:207], v[118:121]
	v_mfma_f32_16x16x32_f16 v[86:89], v[180:183], v[216:219], v[86:89]
	v_mfma_f32_16x16x32_f16 v[102:105], v[184:187], v[216:219], v[102:105]
	v_mfma_f32_16x16x32_f16 v[70:73], v[180:183], v[220:223], v[70:73]
	v_mfma_f32_16x16x32_f16 v[78:81], v[184:187], v[220:223], v[78:81]
	v_mfma_f32_16x16x32_f16 v[122:125], v[188:191], v[208:211], v[122:125]
	v_mfma_f32_16x16x32_f16 v[126:129], v[192:195], v[208:211], v[126:129]
	v_mfma_f32_16x16x32_f16 v[110:113], v[188:191], v[212:215], v[110:113]
	v_mfma_f32_16x16x32_f16 v[118:121], v[192:195], v[212:215], v[118:121]
	v_mfma_f32_16x16x32_f16 v[86:89], v[188:191], v[224:227], v[86:89]
	v_mfma_f32_16x16x32_f16 v[102:105], v[192:195], v[224:227], v[102:105]
	v_mfma_f32_16x16x32_f16 v[70:73], v[188:191], v[228:231], v[70:73]
	v_mfma_f32_16x16x32_f16 v[78:81], v[192:195], v[228:231], v[78:81]
	s_barrier
	ds_read_b128 v[196:199], v161 offset:49152
	ds_read_b128 v[204:207], v161 offset:51200
	ds_read_b128 v[208:211], v162 offset:49152
	ds_read_b128 v[212:215], v162 offset:51200
	ds_read_b128 v[216:219], v161 offset:53248
	ds_read_b128 v[220:223], v161 offset:55296
	ds_read_b128 v[224:227], v162 offset:53248
	ds_read_b128 v[228:231], v162 offset:55296
	s_add_i32 s55, s55, 0x80080
	s_waitcnt vmcnt(0)
	s_waitcnt lgkmcnt(0)
	s_barrier
	s_waitcnt lgkmcnt(0)
	v_mfma_f32_16x16x32_f16 v[54:57], v[164:167], v[196:199], v[54:57]
	v_mfma_f32_16x16x32_f16 v[66:69], v[168:171], v[196:199], v[66:69]
	v_mfma_f32_16x16x32_f16 v[30:33], v[164:167], v[204:207], v[30:33]
	v_mfma_f32_16x16x32_f16 v[38:41], v[168:171], v[204:207], v[38:41]
	v_mfma_f32_16x16x32_f16 v[10:13], v[164:167], v[216:219], v[10:13]
	v_mfma_f32_16x16x32_f16 v[18:21], v[168:171], v[216:219], v[18:21]
	v_mfma_f32_16x16x32_f16 v[2:5], v[164:167], v[220:223], v[2:5]
	v_mfma_f32_16x16x32_f16 v[6:9], v[168:171], v[220:223], v[6:9]
	v_mfma_f32_16x16x32_f16 v[54:57], v[172:175], v[208:211], v[54:57]
	v_mfma_f32_16x16x32_f16 v[66:69], v[176:179], v[208:211], v[66:69]
	v_mfma_f32_16x16x32_f16 v[30:33], v[172:175], v[212:215], v[30:33]
	v_mfma_f32_16x16x32_f16 v[38:41], v[176:179], v[212:215], v[38:41]
	v_mfma_f32_16x16x32_f16 v[10:13], v[172:175], v[224:227], v[10:13]
	v_mfma_f32_16x16x32_f16 v[18:21], v[176:179], v[224:227], v[18:21]
	v_mfma_f32_16x16x32_f16 v[2:5], v[172:175], v[228:231], v[2:5]
	v_mfma_f32_16x16x32_f16 v[6:9], v[176:179], v[228:231], v[6:9]
	v_mfma_f32_16x16x32_f16 v[106:109], v[180:183], v[196:199], v[106:109]
	v_mfma_f32_16x16x32_f16 v[114:117], v[184:187], v[196:199], v[114:117]
	v_mfma_f32_16x16x32_f16 v[82:85], v[180:183], v[204:207], v[82:85]
	v_mfma_f32_16x16x32_f16 v[90:93], v[184:187], v[204:207], v[90:93]
	v_mfma_f32_16x16x32_f16 v[46:49], v[180:183], v[216:219], v[46:49]
	v_mfma_f32_16x16x32_f16 v[58:61], v[184:187], v[216:219], v[58:61]
	v_mfma_f32_16x16x32_f16 v[26:29], v[180:183], v[220:223], v[26:29]
	v_mfma_f32_16x16x32_f16 v[50:53], v[184:187], v[220:223], v[50:53]
	v_mfma_f32_16x16x32_f16 v[106:109], v[188:191], v[208:211], v[106:109]
	v_mfma_f32_16x16x32_f16 v[114:117], v[192:195], v[208:211], v[114:117]
	v_mfma_f32_16x16x32_f16 v[82:85], v[188:191], v[212:215], v[82:85]
	v_mfma_f32_16x16x32_f16 v[90:93], v[192:195], v[212:215], v[90:93]
	v_mfma_f32_16x16x32_f16 v[46:49], v[188:191], v[224:227], v[46:49]
	v_mfma_f32_16x16x32_f16 v[58:61], v[192:195], v[224:227], v[58:61]
	v_mfma_f32_16x16x32_f16 v[26:29], v[188:191], v[228:231], v[26:29]
	v_mfma_f32_16x16x32_f16 v[50:53], v[192:195], v[228:231], v[50:53]
	s_barrier
	s_branch .Lc0b_tail

.Lc0b_norm:
	s_add_i32 s55, s52, 0xfff80080
	s_and_b64 s[10:11], s[10:11], exec
	s_cselect_b32 s60, s46, s55
	s_cselect_b32 s55, s47, s53
	s_add_i32 s10, 0, 0x10000
	v_add_u32_e32 v0, s10, v157
	v_add_u32_e32 v147, s10, v158
	s_add_i32 s10, 0, 0x14000
	ds_read_b128 v[164:167], v0
	ds_read_b128 v[168:171], v0 offset:2048
	ds_read_b128 v[172:175], v147
	ds_read_b128 v[176:179], v147 offset:2048
	v_add_u32_e32 v0, s10, v157
	v_add_u32_e32 v147, s10, v158
	ds_read_b128 v[180:183], v0
	ds_read_b128 v[184:187], v0 offset:2048
	ds_read_b128 v[188:191], v147
	ds_read_b128 v[192:195], v147 offset:2048
	s_or_b32 s56, s60, 0x80
	s_or_b32 s58, s55, 0x80
	s_mov_b32 m0, s37
	ds_read_b128 v[196:199], v161
	ds_read_b128 v[204:207], v161 offset:2048
	ds_read_b128 v[208:211], v162
	ds_read_b128 v[212:215], v162 offset:2048
	ds_read_b128 v[216:219], v161 offset:4096
	ds_read_b128 v[220:223], v161 offset:6144
	ds_read_b128 v[224:227], v162 offset:4096
	ds_read_b128 v[228:231], v162 offset:6144
	buffer_load_dwordx4 v151, s[48:51], s52 offen lds
	s_mov_b32 m0, s38
	s_nop 0
	buffer_load_dwordx4 v155, s[48:51], s52 offen lds
	s_waitcnt vmcnt(8)
	s_waitcnt lgkmcnt(0)
	s_barrier
	s_waitcnt lgkmcnt(0)
	v_mfma_f32_16x16x32_f16 v[94:97], v[164:167], v[196:199], v[94:97]
	v_mfma_f32_16x16x32_f16 v[98:101], v[168:171], v[196:199], v[98:101]
	v_mfma_f32_16x16x32_f16 v[62:65], v[164:167], v[204:207], v[62:65]
	v_mfma_f32_16x16x32_f16 v[74:77], v[168:171], v[204:207], v[74:77]
	v_mfma_f32_16x16x32_f16 v[34:37], v[164:167], v[216:219], v[34:37]
	v_mfma_f32_16x16x32_f16 v[42:45], v[168:171], v[216:219], v[42:45]
	v_mfma_f32_16x16x32_f16 v[14:17], v[164:167], v[220:223], v[14:17]
	v_mfma_f32_16x16x32_f16 v[22:25], v[168:171], v[220:223], v[22:25]
	v_mfma_f32_16x16x32_f16 v[94:97], v[172:175], v[208:211], v[94:97]
	v_mfma_f32_16x16x32_f16 v[98:101], v[176:179], v[208:211], v[98:101]
	v_mfma_f32_16x16x32_f16 v[62:65], v[172:175], v[212:215], v[62:65]
	v_mfma_f32_16x16x32_f16 v[74:77], v[176:179], v[212:215], v[74:77]
	v_mfma_f32_16x16x32_f16 v[34:37], v[172:175], v[224:227], v[34:37]
	v_mfma_f32_16x16x32_f16 v[42:45], v[176:179], v[224:227], v[42:45]
	v_mfma_f32_16x16x32_f16 v[14:17], v[172:175], v[228:231], v[14:17]
	v_mfma_f32_16x16x32_f16 v[22:25], v[176:179], v[228:231], v[22:25]
	v_mfma_f32_16x16x32_f16 v[122:125], v[180:183], v[196:199], v[122:125]
	v_mfma_f32_16x16x32_f16 v[126:129], v[184:187], v[196:199], v[126:129]
	v_mfma_f32_16x16x32_f16 v[110:113], v[180:183], v[204:207], v[110:113]
	v_mfma_f32_16x16x32_f16 v[118:121], v[184:187], v[204:207], v[118:121]
	v_mfma_f32_16x16x32_f16 v[86:89], v[180:183], v[216:219], v[86:89]
	v_mfma_f32_16x16x32_f16 v[102:105], v[184:187], v[216:219], v[102:105]
	v_mfma_f32_16x16x32_f16 v[70:73], v[180:183], v[220:223], v[70:73]
	v_mfma_f32_16x16x32_f16 v[78:81], v[184:187], v[220:223], v[78:81]
	v_mfma_f32_16x16x32_f16 v[122:125], v[188:191], v[208:211], v[122:125]
	v_mfma_f32_16x16x32_f16 v[126:129], v[192:195], v[208:211], v[126:129]
	v_mfma_f32_16x16x32_f16 v[110:113], v[188:191], v[212:215], v[110:113]
	v_mfma_f32_16x16x32_f16 v[118:121], v[192:195], v[212:215], v[118:121]
	v_mfma_f32_16x16x32_f16 v[86:89], v[188:191], v[224:227], v[86:89]
	v_mfma_f32_16x16x32_f16 v[102:105], v[192:195], v[224:227], v[102:105]
	v_mfma_f32_16x16x32_f16 v[70:73], v[188:191], v[228:231], v[70:73]
	v_mfma_f32_16x16x32_f16 v[78:81], v[192:195], v[228:231], v[78:81]
	s_barrier
	s_mov_b32 m0, s2
	s_mov_b32 s10, s50
	s_mov_b32 s11, s51
	ds_read_b128 v[196:199], v161 offset:16384
	ds_read_b128 v[204:207], v161 offset:18432
	ds_read_b128 v[208:211], v162 offset:16384
	ds_read_b128 v[212:215], v162 offset:18432
	ds_read_b128 v[216:219], v161 offset:20480
	ds_read_b128 v[220:223], v161 offset:22528
	ds_read_b128 v[224:227], v162 offset:20480
	ds_read_b128 v[228:231], v162 offset:22528
	buffer_load_dwordx4 v153, s[8:11], s55 offen lds
	s_mov_b32 m0, s3
	s_add_i32 s61, s55, 0x80000
	buffer_load_dwordx4 v156, s[8:11], s55 offen lds
	s_mov_b32 m0, s20
	s_nop 0
	buffer_load_dwordx4 v153, s[8:11], s61 offen lds
	s_mov_b32 m0, s21
	s_nop 0
	buffer_load_dwordx4 v156, s[8:11], s61 offen lds
	s_mov_b32 m0, s1
	s_nop 0
	buffer_load_dwordx4 v151, s[48:51], s60 offen lds
	s_mov_b32 m0, s26
	s_nop 0
	buffer_load_dwordx4 v155, s[48:51], s60 offen lds
	s_waitcnt vmcnt(8)
	s_waitcnt lgkmcnt(0)
	s_barrier
	s_waitcnt lgkmcnt(0)
	v_mfma_f32_16x16x32_f16 v[54:57], v[164:167], v[196:199], v[54:57]
	v_mfma_f32_16x16x32_f16 v[66:69], v[168:171], v[196:199], v[66:69]
	v_mfma_f32_16x16x32_f16 v[30:33], v[164:167], v[204:207], v[30:33]
	v_mfma_f32_16x16x32_f16 v[38:41], v[168:171], v[204:207], v[38:41]
	v_mfma_f32_16x16x32_f16 v[10:13], v[164:167], v[216:219], v[10:13]
	v_mfma_f32_16x16x32_f16 v[18:21], v[168:171], v[216:219], v[18:21]
	v_mfma_f32_16x16x32_f16 v[2:5], v[164:167], v[220:223], v[2:5]
	v_mfma_f32_16x16x32_f16 v[6:9], v[168:171], v[220:223], v[6:9]
	v_mfma_f32_16x16x32_f16 v[54:57], v[172:175], v[208:211], v[54:57]
	v_mfma_f32_16x16x32_f16 v[66:69], v[176:179], v[208:211], v[66:69]
	v_mfma_f32_16x16x32_f16 v[30:33], v[172:175], v[212:215], v[30:33]
	v_mfma_f32_16x16x32_f16 v[38:41], v[176:179], v[212:215], v[38:41]
	v_mfma_f32_16x16x32_f16 v[10:13], v[172:175], v[224:227], v[10:13]
	v_mfma_f32_16x16x32_f16 v[18:21], v[176:179], v[224:227], v[18:21]
	v_mfma_f32_16x16x32_f16 v[2:5], v[172:175], v[228:231], v[2:5]
	v_mfma_f32_16x16x32_f16 v[6:9], v[176:179], v[228:231], v[6:9]
	v_mfma_f32_16x16x32_f16 v[106:109], v[180:183], v[196:199], v[106:109]
	v_mfma_f32_16x16x32_f16 v[114:117], v[184:187], v[196:199], v[114:117]
	v_mfma_f32_16x16x32_f16 v[82:85], v[180:183], v[204:207], v[82:85]
	v_mfma_f32_16x16x32_f16 v[90:93], v[184:187], v[204:207], v[90:93]
	v_mfma_f32_16x16x32_f16 v[46:49], v[180:183], v[216:219], v[46:49]
	v_mfma_f32_16x16x32_f16 v[58:61], v[184:187], v[216:219], v[58:61]
	v_mfma_f32_16x16x32_f16 v[26:29], v[180:183], v[220:223], v[26:29]
	v_mfma_f32_16x16x32_f16 v[50:53], v[184:187], v[220:223], v[50:53]
	v_mfma_f32_16x16x32_f16 v[106:109], v[188:191], v[208:211], v[106:109]
	v_mfma_f32_16x16x32_f16 v[114:117], v[192:195], v[208:211], v[114:117]
	v_mfma_f32_16x16x32_f16 v[82:85], v[188:191], v[212:215], v[82:85]
	v_mfma_f32_16x16x32_f16 v[90:93], v[192:195], v[212:215], v[90:93]
	v_mfma_f32_16x16x32_f16 v[46:49], v[188:191], v[224:227], v[46:49]
	v_mfma_f32_16x16x32_f16 v[58:61], v[192:195], v[224:227], v[58:61]
	v_mfma_f32_16x16x32_f16 v[26:29], v[188:191], v[228:231], v[26:29]
	v_mfma_f32_16x16x32_f16 v[50:53], v[192:195], v[228:231], v[50:53]
	s_barrier
	s_add_i32 s61, 0, 0x18000
	v_add_u32_e32 v0, s61, v157
	v_add_u32_e32 v147, s61, v158
	s_add_i32 s61, 0, 0x1c000
	ds_read_b128 v[164:167], v0
	ds_read_b128 v[168:171], v0 offset:2048
	ds_read_b128 v[172:175], v147
	ds_read_b128 v[176:179], v147 offset:2048
	v_add_u32_e32 v0, s61, v157
	v_add_u32_e32 v147, s61, v158
	ds_read_b128 v[180:183], v0
	ds_read_b128 v[184:187], v0 offset:2048
	ds_read_b128 v[188:191], v147
	ds_read_b128 v[192:195], v147 offset:2048
	s_add_i32 s60, s60, 0x80000
	s_mov_b32 m0, s27
	ds_read_b128 v[196:199], v161 offset:32768
	ds_read_b128 v[204:207], v161 offset:34816
	ds_read_b128 v[208:211], v162 offset:32768
	ds_read_b128 v[212:215], v162 offset:34816
	ds_read_b128 v[216:219], v161 offset:36864
	ds_read_b128 v[220:223], v161 offset:38912
	ds_read_b128 v[224:227], v162 offset:36864
	ds_read_b128 v[228:231], v162 offset:38912
	buffer_load_dwordx4 v151, s[48:51], s60 offen lds
	s_mov_b32 m0, s28
	s_nop 0
	buffer_load_dwordx4 v155, s[48:51], s60 offen lds
	s_waitcnt vmcnt(8)
	s_waitcnt lgkmcnt(0)
	s_barrier
	s_waitcnt lgkmcnt(0)
	v_mfma_f32_16x16x32_f16 v[94:97], v[164:167], v[196:199], v[94:97]
	v_mfma_f32_16x16x32_f16 v[98:101], v[168:171], v[196:199], v[98:101]
	v_mfma_f32_16x16x32_f16 v[62:65], v[164:167], v[204:207], v[62:65]
	v_mfma_f32_16x16x32_f16 v[74:77], v[168:171], v[204:207], v[74:77]
	v_mfma_f32_16x16x32_f16 v[34:37], v[164:167], v[216:219], v[34:37]
	v_mfma_f32_16x16x32_f16 v[42:45], v[168:171], v[216:219], v[42:45]
	v_mfma_f32_16x16x32_f16 v[14:17], v[164:167], v[220:223], v[14:17]
	v_mfma_f32_16x16x32_f16 v[22:25], v[168:171], v[220:223], v[22:25]
	v_mfma_f32_16x16x32_f16 v[94:97], v[172:175], v[208:211], v[94:97]
	v_mfma_f32_16x16x32_f16 v[98:101], v[176:179], v[208:211], v[98:101]
	v_mfma_f32_16x16x32_f16 v[62:65], v[172:175], v[212:215], v[62:65]
	v_mfma_f32_16x16x32_f16 v[74:77], v[176:179], v[212:215], v[74:77]
	v_mfma_f32_16x16x32_f16 v[34:37], v[172:175], v[224:227], v[34:37]
	v_mfma_f32_16x16x32_f16 v[42:45], v[176:179], v[224:227], v[42:45]
	v_mfma_f32_16x16x32_f16 v[14:17], v[172:175], v[228:231], v[14:17]
	v_mfma_f32_16x16x32_f16 v[22:25], v[176:179], v[228:231], v[22:25]
	v_mfma_f32_16x16x32_f16 v[122:125], v[180:183], v[196:199], v[122:125]
	v_mfma_f32_16x16x32_f16 v[126:129], v[184:187], v[196:199], v[126:129]
	v_mfma_f32_16x16x32_f16 v[110:113], v[180:183], v[204:207], v[110:113]
	v_mfma_f32_16x16x32_f16 v[118:121], v[184:187], v[204:207], v[118:121]
	v_mfma_f32_16x16x32_f16 v[86:89], v[180:183], v[216:219], v[86:89]
	v_mfma_f32_16x16x32_f16 v[102:105], v[184:187], v[216:219], v[102:105]
	v_mfma_f32_16x16x32_f16 v[70:73], v[180:183], v[220:223], v[70:73]
	v_mfma_f32_16x16x32_f16 v[78:81], v[184:187], v[220:223], v[78:81]
	v_mfma_f32_16x16x32_f16 v[122:125], v[188:191], v[208:211], v[122:125]
	v_mfma_f32_16x16x32_f16 v[126:129], v[192:195], v[208:211], v[126:129]
	v_mfma_f32_16x16x32_f16 v[110:113], v[188:191], v[212:215], v[110:113]
	v_mfma_f32_16x16x32_f16 v[118:121], v[192:195], v[212:215], v[118:121]
	v_mfma_f32_16x16x32_f16 v[86:89], v[188:191], v[224:227], v[86:89]
	v_mfma_f32_16x16x32_f16 v[102:105], v[192:195], v[224:227], v[102:105]
	v_mfma_f32_16x16x32_f16 v[70:73], v[188:191], v[228:231], v[70:73]
	v_mfma_f32_16x16x32_f16 v[78:81], v[192:195], v[228:231], v[78:81]
	s_barrier
	s_mov_b32 m0, s29
	ds_read_b128 v[196:199], v161 offset:49152
	ds_read_b128 v[204:207], v161 offset:51200
	ds_read_b128 v[208:211], v162 offset:49152
	ds_read_b128 v[212:215], v162 offset:51200
	ds_read_b128 v[216:219], v161 offset:53248
	ds_read_b128 v[220:223], v161 offset:55296
	ds_read_b128 v[224:227], v162 offset:53248
	ds_read_b128 v[228:231], v162 offset:55296
	buffer_load_dwordx4 v153, s[8:11], s58 offen lds
	s_mov_b32 m0, s30
	s_add_i32 s55, s55, 0x80080
	buffer_load_dwordx4 v156, s[8:11], s58 offen lds
	s_mov_b32 m0, s35
	s_nop 0
	buffer_load_dwordx4 v153, s[8:11], s55 offen lds
	s_mov_b32 m0, s36
	s_nop 0
	buffer_load_dwordx4 v156, s[8:11], s55 offen lds
	s_mov_b32 m0, s31
	s_nop 0
	buffer_load_dwordx4 v151, s[48:51], s56 offen lds
	s_mov_b32 m0, s34
	s_nop 0
	buffer_load_dwordx4 v155, s[48:51], s56 offen lds
	s_waitcnt vmcnt(8)
	s_waitcnt lgkmcnt(0)
	s_barrier
	s_waitcnt lgkmcnt(0)
	v_mfma_f32_16x16x32_f16 v[54:57], v[164:167], v[196:199], v[54:57]
	v_mfma_f32_16x16x32_f16 v[66:69], v[168:171], v[196:199], v[66:69]
	v_mfma_f32_16x16x32_f16 v[30:33], v[164:167], v[204:207], v[30:33]
	v_mfma_f32_16x16x32_f16 v[38:41], v[168:171], v[204:207], v[38:41]
	v_mfma_f32_16x16x32_f16 v[10:13], v[164:167], v[216:219], v[10:13]
	v_mfma_f32_16x16x32_f16 v[18:21], v[168:171], v[216:219], v[18:21]
	v_mfma_f32_16x16x32_f16 v[2:5], v[164:167], v[220:223], v[2:5]
	v_mfma_f32_16x16x32_f16 v[6:9], v[168:171], v[220:223], v[6:9]
	v_mfma_f32_16x16x32_f16 v[54:57], v[172:175], v[208:211], v[54:57]
	v_mfma_f32_16x16x32_f16 v[66:69], v[176:179], v[208:211], v[66:69]
	v_mfma_f32_16x16x32_f16 v[30:33], v[172:175], v[212:215], v[30:33]
	v_mfma_f32_16x16x32_f16 v[38:41], v[176:179], v[212:215], v[38:41]
	v_mfma_f32_16x16x32_f16 v[10:13], v[172:175], v[224:227], v[10:13]
	v_mfma_f32_16x16x32_f16 v[18:21], v[176:179], v[224:227], v[18:21]
	v_mfma_f32_16x16x32_f16 v[2:5], v[172:175], v[228:231], v[2:5]
	v_mfma_f32_16x16x32_f16 v[6:9], v[176:179], v[228:231], v[6:9]
	v_mfma_f32_16x16x32_f16 v[106:109], v[180:183], v[196:199], v[106:109]
	v_mfma_f32_16x16x32_f16 v[114:117], v[184:187], v[196:199], v[114:117]
	v_mfma_f32_16x16x32_f16 v[82:85], v[180:183], v[204:207], v[82:85]
	v_mfma_f32_16x16x32_f16 v[90:93], v[184:187], v[204:207], v[90:93]
	v_mfma_f32_16x16x32_f16 v[46:49], v[180:183], v[216:219], v[46:49]
	v_mfma_f32_16x16x32_f16 v[58:61], v[184:187], v[216:219], v[58:61]
	v_mfma_f32_16x16x32_f16 v[26:29], v[180:183], v[220:223], v[26:29]
	v_mfma_f32_16x16x32_f16 v[50:53], v[184:187], v[220:223], v[50:53]
	v_mfma_f32_16x16x32_f16 v[106:109], v[188:191], v[208:211], v[106:109]
	v_mfma_f32_16x16x32_f16 v[114:117], v[192:195], v[208:211], v[114:117]
	v_mfma_f32_16x16x32_f16 v[82:85], v[188:191], v[212:215], v[82:85]
	v_mfma_f32_16x16x32_f16 v[90:93], v[192:195], v[212:215], v[90:93]
	v_mfma_f32_16x16x32_f16 v[46:49], v[188:191], v[224:227], v[46:49]
	v_mfma_f32_16x16x32_f16 v[58:61], v[192:195], v[224:227], v[58:61]
	v_mfma_f32_16x16x32_f16 v[26:29], v[188:191], v[228:231], v[26:29]
	v_mfma_f32_16x16x32_f16 v[50:53], v[192:195], v[228:231], v[50:53]
	s_barrier

.Lc0r_first:
	s_add_i32 s81, s64, 0x80
	s_and_b64 s[10:11], s[10:11], exec
	s_cselect_b32 s84, s24, s81
	s_cselect_b32 s85, s25, s65
	s_add_i32 s10, 0, 0x10000
	v_add_u32_e32 v3, s10, v208
	v_add_u32_e32 v144, s10, v209
	s_add_i32 s10, 0, 0x14000
	ds_read_b128 v[116:119], v3
	ds_read_b128 v[120:123], v3 offset:2048
	ds_read_b128 v[140:143], v144
	ds_read_b128 v[144:147], v144 offset:2048
	v_add_u32_e32 v3, s10, v208
	v_add_u32_e32 v176, s10, v209
	ds_read_b128 v[164:167], v3
	ds_read_b128 v[168:171], v3 offset:2048
	ds_read_b128 v[172:175], v176
	ds_read_b128 v[176:179], v176 offset:2048
	s_add_i32 s81, s84, 0x80
	s_add_i32 s82, s85, 0x80
	s_add_i32 s10, s29, s64
	s_mov_b32 m0, s53
	ds_read_b128 v[180:183], v214
	ds_read_b128 v[184:187], v214 offset:2048
	ds_read_b128 v[188:191], v215
	ds_read_b128 v[192:195], v215 offset:2048
	ds_read_b128 v[196:199], v214 offset:4096
	ds_read_b128 v[216:219], v214 offset:6144
	ds_read_b128 v[220:223], v215 offset:4096
	ds_read_b128 v[224:227], v215 offset:6144
	buffer_load_dwordx4 v204, s[48:51], s10 offen lds
	s_mov_b32 m0, s54
	s_nop 0
	buffer_load_dwordx4 v206, s[48:51], s10 offen lds
	s_waitcnt vmcnt(8)
	s_waitcnt lgkmcnt(0)
	s_barrier
	s_waitcnt lgkmcnt(0)
	v_mfma_f32_16x16x32_bf16 v[160:163], v[116:119], v[180:183], 0
	v_mfma_f32_16x16x32_bf16 v[152:155], v[120:123], v[180:183], 0
	v_mfma_f32_16x16x32_bf16 v[132:135], v[116:119], v[184:187], 0
	v_mfma_f32_16x16x32_bf16 v[124:127], v[120:123], v[184:187], 0
	v_mfma_f32_16x16x32_bf16 v[108:111], v[116:119], v[196:199], 0
	v_mfma_f32_16x16x32_bf16 v[100:103], v[120:123], v[196:199], 0
	v_mfma_f32_16x16x32_bf16 v[92:95], v[116:119], v[216:219], 0
	v_mfma_f32_16x16x32_bf16 v[84:87], v[120:123], v[216:219], 0
	v_mfma_f32_16x16x32_bf16 v[160:163], v[140:143], v[188:191], v[160:163]
	v_mfma_f32_16x16x32_bf16 v[152:155], v[144:147], v[188:191], v[152:155]
	v_mfma_f32_16x16x32_bf16 v[132:135], v[140:143], v[192:195], v[132:135]
	v_mfma_f32_16x16x32_bf16 v[124:127], v[144:147], v[192:195], v[124:127]
	v_mfma_f32_16x16x32_bf16 v[108:111], v[140:143], v[220:223], v[108:111]
	v_mfma_f32_16x16x32_bf16 v[100:103], v[144:147], v[220:223], v[100:103]
	v_mfma_f32_16x16x32_bf16 v[92:95], v[140:143], v[224:227], v[92:95]
	v_mfma_f32_16x16x32_bf16 v[84:87], v[144:147], v[224:227], v[84:87]
	v_mfma_f32_16x16x32_bf16 v[156:159], v[164:167], v[180:183], 0
	v_mfma_f32_16x16x32_bf16 v[148:151], v[168:171], v[180:183], 0
	v_mfma_f32_16x16x32_bf16 v[136:139], v[164:167], v[184:187], 0
	v_mfma_f32_16x16x32_bf16 v[128:131], v[168:171], v[184:187], 0
	v_mfma_f32_16x16x32_bf16 v[112:115], v[164:167], v[196:199], 0
	v_mfma_f32_16x16x32_bf16 v[104:107], v[168:171], v[196:199], 0
	v_mfma_f32_16x16x32_bf16 v[96:99], v[164:167], v[216:219], 0
	v_mfma_f32_16x16x32_bf16 v[88:91], v[168:171], v[216:219], 0
	v_mfma_f32_16x16x32_bf16 v[156:159], v[172:175], v[188:191], v[156:159]
	v_mfma_f32_16x16x32_bf16 v[148:151], v[176:179], v[188:191], v[148:151]
	v_mfma_f32_16x16x32_bf16 v[136:139], v[172:175], v[192:195], v[136:139]
	v_mfma_f32_16x16x32_bf16 v[128:131], v[176:179], v[192:195], v[128:131]
	v_mfma_f32_16x16x32_bf16 v[112:115], v[172:175], v[220:223], v[112:115]
	v_mfma_f32_16x16x32_bf16 v[104:107], v[176:179], v[220:223], v[104:107]
	v_mfma_f32_16x16x32_bf16 v[96:99], v[172:175], v[224:227], v[96:99]
	v_mfma_f32_16x16x32_bf16 v[88:91], v[176:179], v[224:227], v[88:91]
	s_barrier
	s_mov_b32 m0, s34
	s_mov_b32 s10, s50
	s_mov_b32 s11, s51
	ds_read_b128 v[180:183], v214 offset:16384
	ds_read_b128 v[184:187], v214 offset:18432
	ds_read_b128 v[188:191], v215 offset:16384
	ds_read_b128 v[192:195], v215 offset:18432
	ds_read_b128 v[196:199], v214 offset:20480
	ds_read_b128 v[216:219], v214 offset:22528
	ds_read_b128 v[220:223], v215 offset:20480
	ds_read_b128 v[224:227], v215 offset:22528
	buffer_load_dwordx4 v205, s[8:11], s85 offen lds
	s_mov_b32 m0, s35
	s_nop 0
	buffer_load_dwordx4 v207, s[8:11], s85 offen lds
	s_add_i32 s85, s85, s29
	s_mov_b32 m0, s36
	s_nop 0
	buffer_load_dwordx4 v205, s[8:11], s85 offen lds
	s_mov_b32 m0, s37
	s_nop 0
	buffer_load_dwordx4 v207, s[8:11], s85 offen lds
	s_mov_b32 m0, s31
	s_nop 0
	buffer_load_dwordx4 v204, s[48:51], s84 offen lds
	s_mov_b32 m0, s38
	s_nop 0
	buffer_load_dwordx4 v206, s[48:51], s84 offen lds
	s_waitcnt vmcnt(8)
	s_waitcnt lgkmcnt(0)
	s_barrier
	s_waitcnt lgkmcnt(0)
	v_mfma_f32_16x16x32_bf16 v[76:79], v[116:119], v[180:183], 0
	v_mfma_f32_16x16x32_bf16 v[68:71], v[120:123], v[180:183], 0
	v_mfma_f32_16x16x32_bf16 v[60:63], v[116:119], v[184:187], 0
	v_mfma_f32_16x16x32_bf16 v[52:55], v[120:123], v[184:187], 0
	v_mfma_f32_16x16x32_bf16 v[44:47], v[116:119], v[196:199], 0
	v_mfma_f32_16x16x32_bf16 v[36:39], v[120:123], v[196:199], 0
	v_mfma_f32_16x16x32_bf16 v[24:27], v[116:119], v[216:219], 0
	v_mfma_f32_16x16x32_bf16 v[20:23], v[120:123], v[216:219], 0
	v_mfma_f32_16x16x32_bf16 v[76:79], v[140:143], v[188:191], v[76:79]
	v_mfma_f32_16x16x32_bf16 v[68:71], v[144:147], v[188:191], v[68:71]
	v_mfma_f32_16x16x32_bf16 v[60:63], v[140:143], v[192:195], v[60:63]
	v_mfma_f32_16x16x32_bf16 v[52:55], v[144:147], v[192:195], v[52:55]
	v_mfma_f32_16x16x32_bf16 v[44:47], v[140:143], v[220:223], v[44:47]
	v_mfma_f32_16x16x32_bf16 v[36:39], v[144:147], v[220:223], v[36:39]
	v_mfma_f32_16x16x32_bf16 v[24:27], v[140:143], v[224:227], v[24:27]
	v_mfma_f32_16x16x32_bf16 v[20:23], v[144:147], v[224:227], v[20:23]
	v_mfma_f32_16x16x32_bf16 v[80:83], v[164:167], v[180:183], 0
	v_mfma_f32_16x16x32_bf16 v[72:75], v[168:171], v[180:183], 0
	v_mfma_f32_16x16x32_bf16 v[64:67], v[164:167], v[184:187], 0
	v_mfma_f32_16x16x32_bf16 v[56:59], v[168:171], v[184:187], 0
	v_mfma_f32_16x16x32_bf16 v[48:51], v[164:167], v[196:199], 0
	v_mfma_f32_16x16x32_bf16 v[40:43], v[168:171], v[196:199], 0
	v_mfma_f32_16x16x32_bf16 v[28:31], v[164:167], v[216:219], 0
	v_mfma_f32_16x16x32_bf16 v[32:35], v[168:171], v[216:219], 0
	v_mfma_f32_16x16x32_bf16 v[80:83], v[172:175], v[188:191], v[80:83]
	v_mfma_f32_16x16x32_bf16 v[72:75], v[176:179], v[188:191], v[72:75]
	v_mfma_f32_16x16x32_bf16 v[64:67], v[172:175], v[192:195], v[64:67]
	v_mfma_f32_16x16x32_bf16 v[56:59], v[176:179], v[192:195], v[56:59]
	v_mfma_f32_16x16x32_bf16 v[48:51], v[172:175], v[220:223], v[48:51]
	v_mfma_f32_16x16x32_bf16 v[40:43], v[176:179], v[220:223], v[40:43]
	v_mfma_f32_16x16x32_bf16 v[28:31], v[172:175], v[224:227], v[28:31]
	v_mfma_f32_16x16x32_bf16 v[32:35], v[176:179], v[224:227], v[32:35]
	s_barrier
	s_add_i32 s85, 0, 0x18000
	v_add_u32_e32 v3, s85, v208
	v_add_u32_e32 v144, s85, v209
	s_add_i32 s85, 0, 0x1c000
	ds_read_b128 v[116:119], v3
	ds_read_b128 v[120:123], v3 offset:2048
	ds_read_b128 v[140:143], v144
	ds_read_b128 v[144:147], v144 offset:2048
	v_add_u32_e32 v3, s85, v208
	v_add_u32_e32 v176, s85, v209
	ds_read_b128 v[164:167], v3
	ds_read_b128 v[168:171], v3 offset:2048
	ds_read_b128 v[172:175], v176
	ds_read_b128 v[176:179], v176 offset:2048
	s_add_i32 s84, s84, s29
	s_mov_b32 m0, s39
	ds_read_b128 v[180:183], v214 offset:32768
	ds_read_b128 v[184:187], v214 offset:34816
	ds_read_b128 v[188:191], v215 offset:32768
	ds_read_b128 v[192:195], v215 offset:34816
	ds_read_b128 v[196:199], v214 offset:36864
	ds_read_b128 v[216:219], v214 offset:38912
	ds_read_b128 v[220:223], v215 offset:36864
	ds_read_b128 v[224:227], v215 offset:38912
	buffer_load_dwordx4 v204, s[48:51], s84 offen lds
	s_mov_b32 m0, s40
	s_nop 0
	buffer_load_dwordx4 v206, s[48:51], s84 offen lds
	s_waitcnt vmcnt(8)
	s_waitcnt lgkmcnt(0)
	s_barrier
	s_waitcnt lgkmcnt(0)
	v_mfma_f32_16x16x32_bf16 v[160:163], v[116:119], v[180:183], v[160:163]
	v_mfma_f32_16x16x32_bf16 v[152:155], v[120:123], v[180:183], v[152:155]
	v_mfma_f32_16x16x32_bf16 v[132:135], v[116:119], v[184:187], v[132:135]
	v_mfma_f32_16x16x32_bf16 v[124:127], v[120:123], v[184:187], v[124:127]
	v_mfma_f32_16x16x32_bf16 v[108:111], v[116:119], v[196:199], v[108:111]
	v_mfma_f32_16x16x32_bf16 v[100:103], v[120:123], v[196:199], v[100:103]
	v_mfma_f32_16x16x32_bf16 v[92:95], v[116:119], v[216:219], v[92:95]
	v_mfma_f32_16x16x32_bf16 v[84:87], v[120:123], v[216:219], v[84:87]
	v_mfma_f32_16x16x32_bf16 v[160:163], v[140:143], v[188:191], v[160:163]
	v_mfma_f32_16x16x32_bf16 v[152:155], v[144:147], v[188:191], v[152:155]
	v_mfma_f32_16x16x32_bf16 v[132:135], v[140:143], v[192:195], v[132:135]
	v_mfma_f32_16x16x32_bf16 v[124:127], v[144:147], v[192:195], v[124:127]
	v_mfma_f32_16x16x32_bf16 v[108:111], v[140:143], v[220:223], v[108:111]
	v_mfma_f32_16x16x32_bf16 v[100:103], v[144:147], v[220:223], v[100:103]
	v_mfma_f32_16x16x32_bf16 v[92:95], v[140:143], v[224:227], v[92:95]
	v_mfma_f32_16x16x32_bf16 v[84:87], v[144:147], v[224:227], v[84:87]
	v_mfma_f32_16x16x32_bf16 v[156:159], v[164:167], v[180:183], v[156:159]
	v_mfma_f32_16x16x32_bf16 v[148:151], v[168:171], v[180:183], v[148:151]
	v_mfma_f32_16x16x32_bf16 v[136:139], v[164:167], v[184:187], v[136:139]
	v_mfma_f32_16x16x32_bf16 v[128:131], v[168:171], v[184:187], v[128:131]
	v_mfma_f32_16x16x32_bf16 v[112:115], v[164:167], v[196:199], v[112:115]
	v_mfma_f32_16x16x32_bf16 v[104:107], v[168:171], v[196:199], v[104:107]
	v_mfma_f32_16x16x32_bf16 v[96:99], v[164:167], v[216:219], v[96:99]
	v_mfma_f32_16x16x32_bf16 v[88:91], v[168:171], v[216:219], v[88:91]
	v_mfma_f32_16x16x32_bf16 v[156:159], v[172:175], v[188:191], v[156:159]
	v_mfma_f32_16x16x32_bf16 v[148:151], v[176:179], v[188:191], v[148:151]
	v_mfma_f32_16x16x32_bf16 v[136:139], v[172:175], v[192:195], v[136:139]
	v_mfma_f32_16x16x32_bf16 v[128:131], v[176:179], v[192:195], v[128:131]
	v_mfma_f32_16x16x32_bf16 v[112:115], v[172:175], v[220:223], v[112:115]
	v_mfma_f32_16x16x32_bf16 v[104:107], v[176:179], v[220:223], v[104:107]
	v_mfma_f32_16x16x32_bf16 v[96:99], v[172:175], v[224:227], v[96:99]
	v_mfma_f32_16x16x32_bf16 v[88:91], v[176:179], v[224:227], v[88:91]
	s_barrier
	s_mov_b32 m0, s41
	ds_read_b128 v[180:183], v214 offset:49152
	ds_read_b128 v[184:187], v214 offset:51200
	ds_read_b128 v[188:191], v215 offset:49152
	ds_read_b128 v[192:195], v215 offset:51200
	ds_read_b128 v[196:199], v214 offset:53248
	ds_read_b128 v[216:219], v214 offset:55296
	ds_read_b128 v[220:223], v215 offset:53248
	ds_read_b128 v[224:227], v215 offset:55296
	buffer_load_dwordx4 v205, s[8:11], s82 offen lds
	s_mov_b32 m0, s42
	s_nop 0
	buffer_load_dwordx4 v207, s[8:11], s82 offen lds
	s_add_i32 s82, s82, s29
	s_mov_b32 m0, s45
	s_nop 0
	buffer_load_dwordx4 v205, s[8:11], s82 offen lds
	s_mov_b32 m0, s46
	s_nop 0
	buffer_load_dwordx4 v207, s[8:11], s82 offen lds
	s_mov_b32 m0, s43
	s_nop 0
	buffer_load_dwordx4 v204, s[48:51], s81 offen lds
	s_mov_b32 m0, s44
	s_nop 0
	buffer_load_dwordx4 v206, s[48:51], s81 offen lds
	s_waitcnt vmcnt(8)
	s_waitcnt lgkmcnt(0)
	s_barrier
	s_waitcnt lgkmcnt(0)
	v_mfma_f32_16x16x32_bf16 v[76:79], v[116:119], v[180:183], v[76:79]
	v_mfma_f32_16x16x32_bf16 v[68:71], v[120:123], v[180:183], v[68:71]
	v_mfma_f32_16x16x32_bf16 v[60:63], v[116:119], v[184:187], v[60:63]
	v_mfma_f32_16x16x32_bf16 v[52:55], v[120:123], v[184:187], v[52:55]
	v_mfma_f32_16x16x32_bf16 v[44:47], v[116:119], v[196:199], v[44:47]
	v_mfma_f32_16x16x32_bf16 v[36:39], v[120:123], v[196:199], v[36:39]
	v_mfma_f32_16x16x32_bf16 v[24:27], v[116:119], v[216:219], v[24:27]
	v_mfma_f32_16x16x32_bf16 v[20:23], v[120:123], v[216:219], v[20:23]
	v_mfma_f32_16x16x32_bf16 v[76:79], v[140:143], v[188:191], v[76:79]
	v_mfma_f32_16x16x32_bf16 v[68:71], v[144:147], v[188:191], v[68:71]
	v_mfma_f32_16x16x32_bf16 v[60:63], v[140:143], v[192:195], v[60:63]
	v_mfma_f32_16x16x32_bf16 v[52:55], v[144:147], v[192:195], v[52:55]
	v_mfma_f32_16x16x32_bf16 v[44:47], v[140:143], v[220:223], v[44:47]
	v_mfma_f32_16x16x32_bf16 v[36:39], v[144:147], v[220:223], v[36:39]
	v_mfma_f32_16x16x32_bf16 v[24:27], v[140:143], v[224:227], v[24:27]
	v_mfma_f32_16x16x32_bf16 v[20:23], v[144:147], v[224:227], v[20:23]
	v_mfma_f32_16x16x32_bf16 v[80:83], v[164:167], v[180:183], v[80:83]
	v_mfma_f32_16x16x32_bf16 v[72:75], v[168:171], v[180:183], v[72:75]
	v_mfma_f32_16x16x32_bf16 v[64:67], v[164:167], v[184:187], v[64:67]
	v_mfma_f32_16x16x32_bf16 v[56:59], v[168:171], v[184:187], v[56:59]
	v_mfma_f32_16x16x32_bf16 v[48:51], v[164:167], v[196:199], v[48:51]
	v_mfma_f32_16x16x32_bf16 v[40:43], v[168:171], v[196:199], v[40:43]
	v_mfma_f32_16x16x32_bf16 v[28:31], v[164:167], v[216:219], v[28:31]
	v_mfma_f32_16x16x32_bf16 v[32:35], v[168:171], v[216:219], v[32:35]
	v_mfma_f32_16x16x32_bf16 v[80:83], v[172:175], v[188:191], v[80:83]
	v_mfma_f32_16x16x32_bf16 v[72:75], v[176:179], v[188:191], v[72:75]
	v_mfma_f32_16x16x32_bf16 v[64:67], v[172:175], v[192:195], v[64:67]
	v_mfma_f32_16x16x32_bf16 v[56:59], v[176:179], v[192:195], v[56:59]
	v_mfma_f32_16x16x32_bf16 v[48:51], v[172:175], v[220:223], v[48:51]
	v_mfma_f32_16x16x32_bf16 v[40:43], v[176:179], v[220:223], v[40:43]
	v_mfma_f32_16x16x32_bf16 v[28:31], v[172:175], v[224:227], v[28:31]
	v_mfma_f32_16x16x32_bf16 v[32:35], v[176:179], v[224:227], v[32:35]
	s_barrier
	s_branch .Lc0r_tail
.Lc0r_final:
	s_add_i32 s81, s64, 0x80
	s_and_b64 s[10:11], s[10:11], exec
	s_cselect_b32 s84, s24, s81
	s_cselect_b32 s85, s25, s65
	s_add_i32 s10, 0, 0x10000
	v_add_u32_e32 v3, s10, v208
	v_add_u32_e32 v144, s10, v209
	s_add_i32 s10, 0, 0x14000
	ds_read_b128 v[116:119], v3
	ds_read_b128 v[120:123], v3 offset:2048
	ds_read_b128 v[140:143], v144
	ds_read_b128 v[144:147], v144 offset:2048
	v_add_u32_e32 v3, s10, v208
	v_add_u32_e32 v176, s10, v209
	ds_read_b128 v[164:167], v3
	ds_read_b128 v[168:171], v3 offset:2048
	ds_read_b128 v[172:175], v176
	ds_read_b128 v[176:179], v176 offset:2048
	s_add_i32 s81, s84, 0x80
	s_add_i32 s82, s85, 0x80
	s_add_i32 s10, s29, s64
	s_mov_b32 m0, s53
	ds_read_b128 v[180:183], v214
	ds_read_b128 v[184:187], v214 offset:2048
	ds_read_b128 v[188:191], v215
	ds_read_b128 v[192:195], v215 offset:2048
	ds_read_b128 v[196:199], v214 offset:4096
	ds_read_b128 v[216:219], v214 offset:6144
	ds_read_b128 v[220:223], v215 offset:4096
	ds_read_b128 v[224:227], v215 offset:6144
	buffer_load_dwordx4 v204, s[48:51], s10 offen lds
	s_mov_b32 m0, s54
	s_nop 0
	buffer_load_dwordx4 v206, s[48:51], s10 offen lds
	s_waitcnt vmcnt(8)
	s_waitcnt lgkmcnt(0)
	s_barrier
	s_waitcnt lgkmcnt(0)
	v_mfma_f32_16x16x32_bf16 v[160:163], v[116:119], v[180:183], v[160:163]
	v_mfma_f32_16x16x32_bf16 v[152:155], v[120:123], v[180:183], v[152:155]
	v_mfma_f32_16x16x32_bf16 v[132:135], v[116:119], v[184:187], v[132:135]
	v_mfma_f32_16x16x32_bf16 v[124:127], v[120:123], v[184:187], v[124:127]
	v_mfma_f32_16x16x32_bf16 v[108:111], v[116:119], v[196:199], v[108:111]
	v_mfma_f32_16x16x32_bf16 v[100:103], v[120:123], v[196:199], v[100:103]
	v_mfma_f32_16x16x32_bf16 v[92:95], v[116:119], v[216:219], v[92:95]
	v_mfma_f32_16x16x32_bf16 v[84:87], v[120:123], v[216:219], v[84:87]
	v_mfma_f32_16x16x32_bf16 v[160:163], v[140:143], v[188:191], v[160:163]
	v_mfma_f32_16x16x32_bf16 v[152:155], v[144:147], v[188:191], v[152:155]
	v_mfma_f32_16x16x32_bf16 v[132:135], v[140:143], v[192:195], v[132:135]
	v_mfma_f32_16x16x32_bf16 v[124:127], v[144:147], v[192:195], v[124:127]
	v_mfma_f32_16x16x32_bf16 v[108:111], v[140:143], v[220:223], v[108:111]
	v_mfma_f32_16x16x32_bf16 v[100:103], v[144:147], v[220:223], v[100:103]
	v_mfma_f32_16x16x32_bf16 v[92:95], v[140:143], v[224:227], v[92:95]
	v_mfma_f32_16x16x32_bf16 v[84:87], v[144:147], v[224:227], v[84:87]
	v_mfma_f32_16x16x32_bf16 v[156:159], v[164:167], v[180:183], v[156:159]
	v_mfma_f32_16x16x32_bf16 v[148:151], v[168:171], v[180:183], v[148:151]
	v_mfma_f32_16x16x32_bf16 v[136:139], v[164:167], v[184:187], v[136:139]
	v_mfma_f32_16x16x32_bf16 v[128:131], v[168:171], v[184:187], v[128:131]
	v_mfma_f32_16x16x32_bf16 v[112:115], v[164:167], v[196:199], v[112:115]
	v_mfma_f32_16x16x32_bf16 v[104:107], v[168:171], v[196:199], v[104:107]
	v_mfma_f32_16x16x32_bf16 v[96:99], v[164:167], v[216:219], v[96:99]
	v_mfma_f32_16x16x32_bf16 v[88:91], v[168:171], v[216:219], v[88:91]
	v_mfma_f32_16x16x32_bf16 v[156:159], v[172:175], v[188:191], v[156:159]
	v_mfma_f32_16x16x32_bf16 v[148:151], v[176:179], v[188:191], v[148:151]
	v_mfma_f32_16x16x32_bf16 v[136:139], v[172:175], v[192:195], v[136:139]
	v_mfma_f32_16x16x32_bf16 v[128:131], v[176:179], v[192:195], v[128:131]
	v_mfma_f32_16x16x32_bf16 v[112:115], v[172:175], v[220:223], v[112:115]
	v_mfma_f32_16x16x32_bf16 v[104:107], v[176:179], v[220:223], v[104:107]
	v_mfma_f32_16x16x32_bf16 v[96:99], v[172:175], v[224:227], v[96:99]
	v_mfma_f32_16x16x32_bf16 v[88:91], v[176:179], v[224:227], v[88:91]
	s_barrier
	s_mov_b32 s10, s50
	s_mov_b32 s11, s51
	ds_read_b128 v[180:183], v214 offset:16384
	ds_read_b128 v[184:187], v214 offset:18432
	ds_read_b128 v[188:191], v215 offset:16384
	ds_read_b128 v[192:195], v215 offset:18432
	ds_read_b128 v[196:199], v214 offset:20480
	ds_read_b128 v[216:219], v214 offset:22528
	ds_read_b128 v[220:223], v215 offset:20480
	ds_read_b128 v[224:227], v215 offset:22528
	s_add_i32 s85, s85, s29
	s_waitcnt vmcnt(2)
	s_waitcnt lgkmcnt(0)
	s_barrier
	s_waitcnt lgkmcnt(0)
	v_mfma_f32_16x16x32_bf16 v[76:79], v[116:119], v[180:183], v[76:79]
	v_mfma_f32_16x16x32_bf16 v[68:71], v[120:123], v[180:183], v[68:71]
	v_mfma_f32_16x16x32_bf16 v[60:63], v[116:119], v[184:187], v[60:63]
	v_mfma_f32_16x16x32_bf16 v[52:55], v[120:123], v[184:187], v[52:55]
	v_mfma_f32_16x16x32_bf16 v[44:47], v[116:119], v[196:199], v[44:47]
	v_mfma_f32_16x16x32_bf16 v[36:39], v[120:123], v[196:199], v[36:39]
	v_mfma_f32_16x16x32_bf16 v[24:27], v[116:119], v[216:219], v[24:27]
	v_mfma_f32_16x16x32_bf16 v[20:23], v[120:123], v[216:219], v[20:23]
	v_mfma_f32_16x16x32_bf16 v[76:79], v[140:143], v[188:191], v[76:79]
	v_mfma_f32_16x16x32_bf16 v[68:71], v[144:147], v[188:191], v[68:71]
	v_mfma_f32_16x16x32_bf16 v[60:63], v[140:143], v[192:195], v[60:63]
	v_mfma_f32_16x16x32_bf16 v[52:55], v[144:147], v[192:195], v[52:55]
	v_mfma_f32_16x16x32_bf16 v[44:47], v[140:143], v[220:223], v[44:47]
	v_mfma_f32_16x16x32_bf16 v[36:39], v[144:147], v[220:223], v[36:39]
	v_mfma_f32_16x16x32_bf16 v[24:27], v[140:143], v[224:227], v[24:27]
	v_mfma_f32_16x16x32_bf16 v[20:23], v[144:147], v[224:227], v[20:23]
	v_mfma_f32_16x16x32_bf16 v[80:83], v[164:167], v[180:183], v[80:83]
	v_mfma_f32_16x16x32_bf16 v[72:75], v[168:171], v[180:183], v[72:75]
	v_mfma_f32_16x16x32_bf16 v[64:67], v[164:167], v[184:187], v[64:67]
	v_mfma_f32_16x16x32_bf16 v[56:59], v[168:171], v[184:187], v[56:59]
	v_mfma_f32_16x16x32_bf16 v[48:51], v[164:167], v[196:199], v[48:51]
	v_mfma_f32_16x16x32_bf16 v[40:43], v[168:171], v[196:199], v[40:43]
	v_mfma_f32_16x16x32_bf16 v[28:31], v[164:167], v[216:219], v[28:31]
	v_mfma_f32_16x16x32_bf16 v[32:35], v[168:171], v[216:219], v[32:35]
	v_mfma_f32_16x16x32_bf16 v[80:83], v[172:175], v[188:191], v[80:83]
	v_mfma_f32_16x16x32_bf16 v[72:75], v[176:179], v[188:191], v[72:75]
	v_mfma_f32_16x16x32_bf16 v[64:67], v[172:175], v[192:195], v[64:67]
	v_mfma_f32_16x16x32_bf16 v[56:59], v[176:179], v[192:195], v[56:59]
	v_mfma_f32_16x16x32_bf16 v[48:51], v[172:175], v[220:223], v[48:51]
	v_mfma_f32_16x16x32_bf16 v[40:43], v[176:179], v[220:223], v[40:43]
	v_mfma_f32_16x16x32_bf16 v[28:31], v[172:175], v[224:227], v[28:31]
	v_mfma_f32_16x16x32_bf16 v[32:35], v[176:179], v[224:227], v[32:35]
	s_barrier
	s_add_i32 s85, 0, 0x18000
	v_add_u32_e32 v3, s85, v208
	v_add_u32_e32 v144, s85, v209
	s_add_i32 s85, 0, 0x1c000
	ds_read_b128 v[116:119], v3
	ds_read_b128 v[120:123], v3 offset:2048
	ds_read_b128 v[140:143], v144
	ds_read_b128 v[144:147], v144 offset:2048
	v_add_u32_e32 v3, s85, v208
	v_add_u32_e32 v176, s85, v209
	ds_read_b128 v[164:167], v3
	ds_read_b128 v[168:171], v3 offset:2048
	ds_read_b128 v[172:175], v176
	ds_read_b128 v[176:179], v176 offset:2048
	s_add_i32 s84, s84, s29
	ds_read_b128 v[180:183], v214 offset:32768
	ds_read_b128 v[184:187], v214 offset:34816
	ds_read_b128 v[188:191], v215 offset:32768
	ds_read_b128 v[192:195], v215 offset:34816
	ds_read_b128 v[196:199], v214 offset:36864
	ds_read_b128 v[216:219], v214 offset:38912
	ds_read_b128 v[220:223], v215 offset:36864
	ds_read_b128 v[224:227], v215 offset:38912
	s_waitcnt vmcnt(0)
	s_waitcnt lgkmcnt(0)
	s_barrier
	s_waitcnt lgkmcnt(0)
	v_mfma_f32_16x16x32_bf16 v[160:163], v[116:119], v[180:183], v[160:163]
	v_mfma_f32_16x16x32_bf16 v[152:155], v[120:123], v[180:183], v[152:155]
	v_mfma_f32_16x16x32_bf16 v[132:135], v[116:119], v[184:187], v[132:135]
	v_mfma_f32_16x16x32_bf16 v[124:127], v[120:123], v[184:187], v[124:127]
	v_mfma_f32_16x16x32_bf16 v[108:111], v[116:119], v[196:199], v[108:111]
	v_mfma_f32_16x16x32_bf16 v[100:103], v[120:123], v[196:199], v[100:103]
	v_mfma_f32_16x16x32_bf16 v[92:95], v[116:119], v[216:219], v[92:95]
	v_mfma_f32_16x16x32_bf16 v[84:87], v[120:123], v[216:219], v[84:87]
	v_mfma_f32_16x16x32_bf16 v[160:163], v[140:143], v[188:191], v[160:163]
	v_mfma_f32_16x16x32_bf16 v[152:155], v[144:147], v[188:191], v[152:155]
	v_mfma_f32_16x16x32_bf16 v[132:135], v[140:143], v[192:195], v[132:135]
	v_mfma_f32_16x16x32_bf16 v[124:127], v[144:147], v[192:195], v[124:127]
	v_mfma_f32_16x16x32_bf16 v[108:111], v[140:143], v[220:223], v[108:111]
	v_mfma_f32_16x16x32_bf16 v[100:103], v[144:147], v[220:223], v[100:103]
	v_mfma_f32_16x16x32_bf16 v[92:95], v[140:143], v[224:227], v[92:95]
	v_mfma_f32_16x16x32_bf16 v[84:87], v[144:147], v[224:227], v[84:87]
	v_mfma_f32_16x16x32_bf16 v[156:159], v[164:167], v[180:183], v[156:159]
	v_mfma_f32_16x16x32_bf16 v[148:151], v[168:171], v[180:183], v[148:151]
	v_mfma_f32_16x16x32_bf16 v[136:139], v[164:167], v[184:187], v[136:139]
	v_mfma_f32_16x16x32_bf16 v[128:131], v[168:171], v[184:187], v[128:131]
	v_mfma_f32_16x16x32_bf16 v[112:115], v[164:167], v[196:199], v[112:115]
	v_mfma_f32_16x16x32_bf16 v[104:107], v[168:171], v[196:199], v[104:107]
	v_mfma_f32_16x16x32_bf16 v[96:99], v[164:167], v[216:219], v[96:99]
	v_mfma_f32_16x16x32_bf16 v[88:91], v[168:171], v[216:219], v[88:91]
	v_mfma_f32_16x16x32_bf16 v[156:159], v[172:175], v[188:191], v[156:159]
	v_mfma_f32_16x16x32_bf16 v[148:151], v[176:179], v[188:191], v[148:151]
	v_mfma_f32_16x16x32_bf16 v[136:139], v[172:175], v[192:195], v[136:139]
	v_mfma_f32_16x16x32_bf16 v[128:131], v[176:179], v[192:195], v[128:131]
	v_mfma_f32_16x16x32_bf16 v[112:115], v[172:175], v[220:223], v[112:115]
	v_mfma_f32_16x16x32_bf16 v[104:107], v[176:179], v[220:223], v[104:107]
	v_mfma_f32_16x16x32_bf16 v[96:99], v[172:175], v[224:227], v[96:99]
	v_mfma_f32_16x16x32_bf16 v[88:91], v[176:179], v[224:227], v[88:91]
	s_barrier
	ds_read_b128 v[180:183], v214 offset:49152
	ds_read_b128 v[184:187], v214 offset:51200
	ds_read_b128 v[188:191], v215 offset:49152
	ds_read_b128 v[192:195], v215 offset:51200
	ds_read_b128 v[196:199], v214 offset:53248
	ds_read_b128 v[216:219], v214 offset:55296
	ds_read_b128 v[220:223], v215 offset:53248
	ds_read_b128 v[224:227], v215 offset:55296
	s_add_i32 s82, s82, s29
	s_waitcnt vmcnt(0)
	s_waitcnt lgkmcnt(0)
	s_barrier
	s_waitcnt lgkmcnt(0)
	v_mfma_f32_16x16x32_bf16 v[76:79], v[116:119], v[180:183], v[76:79]
	v_mfma_f32_16x16x32_bf16 v[68:71], v[120:123], v[180:183], v[68:71]
	v_mfma_f32_16x16x32_bf16 v[60:63], v[116:119], v[184:187], v[60:63]
	v_mfma_f32_16x16x32_bf16 v[52:55], v[120:123], v[184:187], v[52:55]
	v_mfma_f32_16x16x32_bf16 v[44:47], v[116:119], v[196:199], v[44:47]
	v_mfma_f32_16x16x32_bf16 v[36:39], v[120:123], v[196:199], v[36:39]
	v_mfma_f32_16x16x32_bf16 v[24:27], v[116:119], v[216:219], v[24:27]
	v_mfma_f32_16x16x32_bf16 v[20:23], v[120:123], v[216:219], v[20:23]
	v_mfma_f32_16x16x32_bf16 v[76:79], v[140:143], v[188:191], v[76:79]
	v_mfma_f32_16x16x32_bf16 v[68:71], v[144:147], v[188:191], v[68:71]
	v_mfma_f32_16x16x32_bf16 v[60:63], v[140:143], v[192:195], v[60:63]
	v_mfma_f32_16x16x32_bf16 v[52:55], v[144:147], v[192:195], v[52:55]
	v_mfma_f32_16x16x32_bf16 v[44:47], v[140:143], v[220:223], v[44:47]
	v_mfma_f32_16x16x32_bf16 v[36:39], v[144:147], v[220:223], v[36:39]
	v_mfma_f32_16x16x32_bf16 v[24:27], v[140:143], v[224:227], v[24:27]
	v_mfma_f32_16x16x32_bf16 v[20:23], v[144:147], v[224:227], v[20:23]
	v_mfma_f32_16x16x32_bf16 v[80:83], v[164:167], v[180:183], v[80:83]
	v_mfma_f32_16x16x32_bf16 v[72:75], v[168:171], v[180:183], v[72:75]
	v_mfma_f32_16x16x32_bf16 v[64:67], v[164:167], v[184:187], v[64:67]
	v_mfma_f32_16x16x32_bf16 v[56:59], v[168:171], v[184:187], v[56:59]
	v_mfma_f32_16x16x32_bf16 v[48:51], v[164:167], v[196:199], v[48:51]
	v_mfma_f32_16x16x32_bf16 v[40:43], v[168:171], v[196:199], v[40:43]
	v_mfma_f32_16x16x32_bf16 v[28:31], v[164:167], v[216:219], v[28:31]
	v_mfma_f32_16x16x32_bf16 v[32:35], v[168:171], v[216:219], v[32:35]
	v_mfma_f32_16x16x32_bf16 v[80:83], v[172:175], v[188:191], v[80:83]
	v_mfma_f32_16x16x32_bf16 v[72:75], v[176:179], v[188:191], v[72:75]
	v_mfma_f32_16x16x32_bf16 v[64:67], v[172:175], v[192:195], v[64:67]
	v_mfma_f32_16x16x32_bf16 v[56:59], v[176:179], v[192:195], v[56:59]
	v_mfma_f32_16x16x32_bf16 v[48:51], v[172:175], v[220:223], v[48:51]
	v_mfma_f32_16x16x32_bf16 v[40:43], v[176:179], v[220:223], v[40:43]
	v_mfma_f32_16x16x32_bf16 v[28:31], v[172:175], v[224:227], v[28:31]
	v_mfma_f32_16x16x32_bf16 v[32:35], v[176:179], v[224:227], v[32:35]
	s_barrier
	s_branch .Lc0r_tail

.Lc0r_norm:
	s_add_i32 s81, s64, 0x80
	s_and_b64 s[10:11], s[10:11], exec
	s_cselect_b32 s84, s24, s81
	s_cselect_b32 s85, s25, s65
	s_add_i32 s10, 0, 0x10000
	v_add_u32_e32 v3, s10, v208
	v_add_u32_e32 v144, s10, v209
	s_add_i32 s10, 0, 0x14000
	ds_read_b128 v[116:119], v3
	ds_read_b128 v[120:123], v3 offset:2048
	ds_read_b128 v[140:143], v144
	ds_read_b128 v[144:147], v144 offset:2048
	v_add_u32_e32 v3, s10, v208
	v_add_u32_e32 v176, s10, v209
	ds_read_b128 v[164:167], v3
	ds_read_b128 v[168:171], v3 offset:2048
	ds_read_b128 v[172:175], v176
	ds_read_b128 v[176:179], v176 offset:2048
	s_add_i32 s81, s84, 0x80
	s_add_i32 s82, s85, 0x80
	s_add_i32 s10, s29, s64
	s_mov_b32 m0, s53
	ds_read_b128 v[180:183], v214
	ds_read_b128 v[184:187], v214 offset:2048
	ds_read_b128 v[188:191], v215
	ds_read_b128 v[192:195], v215 offset:2048
	ds_read_b128 v[196:199], v214 offset:4096
	ds_read_b128 v[216:219], v214 offset:6144
	ds_read_b128 v[220:223], v215 offset:4096
	ds_read_b128 v[224:227], v215 offset:6144
	buffer_load_dwordx4 v204, s[48:51], s10 offen lds
	s_mov_b32 m0, s54
	s_nop 0
	buffer_load_dwordx4 v206, s[48:51], s10 offen lds
	s_waitcnt vmcnt(8)
	s_waitcnt lgkmcnt(0)
	s_barrier
	s_waitcnt lgkmcnt(0)
	v_mfma_f32_16x16x32_bf16 v[160:163], v[116:119], v[180:183], v[160:163]
	v_mfma_f32_16x16x32_bf16 v[152:155], v[120:123], v[180:183], v[152:155]
	v_mfma_f32_16x16x32_bf16 v[132:135], v[116:119], v[184:187], v[132:135]
	v_mfma_f32_16x16x32_bf16 v[124:127], v[120:123], v[184:187], v[124:127]
	v_mfma_f32_16x16x32_bf16 v[108:111], v[116:119], v[196:199], v[108:111]
	v_mfma_f32_16x16x32_bf16 v[100:103], v[120:123], v[196:199], v[100:103]
	v_mfma_f32_16x16x32_bf16 v[92:95], v[116:119], v[216:219], v[92:95]
	v_mfma_f32_16x16x32_bf16 v[84:87], v[120:123], v[216:219], v[84:87]
	v_mfma_f32_16x16x32_bf16 v[160:163], v[140:143], v[188:191], v[160:163]
	v_mfma_f32_16x16x32_bf16 v[152:155], v[144:147], v[188:191], v[152:155]
	v_mfma_f32_16x16x32_bf16 v[132:135], v[140:143], v[192:195], v[132:135]
	v_mfma_f32_16x16x32_bf16 v[124:127], v[144:147], v[192:195], v[124:127]
	v_mfma_f32_16x16x32_bf16 v[108:111], v[140:143], v[220:223], v[108:111]
	v_mfma_f32_16x16x32_bf16 v[100:103], v[144:147], v[220:223], v[100:103]
	v_mfma_f32_16x16x32_bf16 v[92:95], v[140:143], v[224:227], v[92:95]
	v_mfma_f32_16x16x32_bf16 v[84:87], v[144:147], v[224:227], v[84:87]
	v_mfma_f32_16x16x32_bf16 v[156:159], v[164:167], v[180:183], v[156:159]
	v_mfma_f32_16x16x32_bf16 v[148:151], v[168:171], v[180:183], v[148:151]
	v_mfma_f32_16x16x32_bf16 v[136:139], v[164:167], v[184:187], v[136:139]
	v_mfma_f32_16x16x32_bf16 v[128:131], v[168:171], v[184:187], v[128:131]
	v_mfma_f32_16x16x32_bf16 v[112:115], v[164:167], v[196:199], v[112:115]
	v_mfma_f32_16x16x32_bf16 v[104:107], v[168:171], v[196:199], v[104:107]
	v_mfma_f32_16x16x32_bf16 v[96:99], v[164:167], v[216:219], v[96:99]
	v_mfma_f32_16x16x32_bf16 v[88:91], v[168:171], v[216:219], v[88:91]
	v_mfma_f32_16x16x32_bf16 v[156:159], v[172:175], v[188:191], v[156:159]
	v_mfma_f32_16x16x32_bf16 v[148:151], v[176:179], v[188:191], v[148:151]
	v_mfma_f32_16x16x32_bf16 v[136:139], v[172:175], v[192:195], v[136:139]
	v_mfma_f32_16x16x32_bf16 v[128:131], v[176:179], v[192:195], v[128:131]
	v_mfma_f32_16x16x32_bf16 v[112:115], v[172:175], v[220:223], v[112:115]
	v_mfma_f32_16x16x32_bf16 v[104:107], v[176:179], v[220:223], v[104:107]
	v_mfma_f32_16x16x32_bf16 v[96:99], v[172:175], v[224:227], v[96:99]
	v_mfma_f32_16x16x32_bf16 v[88:91], v[176:179], v[224:227], v[88:91]
	s_barrier
	s_mov_b32 m0, s34
	s_mov_b32 s10, s50
	s_mov_b32 s11, s51
	ds_read_b128 v[180:183], v214 offset:16384
	ds_read_b128 v[184:187], v214 offset:18432
	ds_read_b128 v[188:191], v215 offset:16384
	ds_read_b128 v[192:195], v215 offset:18432
	ds_read_b128 v[196:199], v214 offset:20480
	ds_read_b128 v[216:219], v214 offset:22528
	ds_read_b128 v[220:223], v215 offset:20480
	ds_read_b128 v[224:227], v215 offset:22528
	buffer_load_dwordx4 v205, s[8:11], s85 offen lds
	s_mov_b32 m0, s35
	s_nop 0
	buffer_load_dwordx4 v207, s[8:11], s85 offen lds
	s_add_i32 s85, s85, s29
	s_mov_b32 m0, s36
	s_nop 0
	buffer_load_dwordx4 v205, s[8:11], s85 offen lds
	s_mov_b32 m0, s37
	s_nop 0
	buffer_load_dwordx4 v207, s[8:11], s85 offen lds
	s_mov_b32 m0, s31
	s_nop 0
	buffer_load_dwordx4 v204, s[48:51], s84 offen lds
	s_mov_b32 m0, s38
	s_nop 0
	buffer_load_dwordx4 v206, s[48:51], s84 offen lds
	s_waitcnt vmcnt(8)
	s_waitcnt lgkmcnt(0)
	s_barrier
	s_waitcnt lgkmcnt(0)
	v_mfma_f32_16x16x32_bf16 v[76:79], v[116:119], v[180:183], v[76:79]
	v_mfma_f32_16x16x32_bf16 v[68:71], v[120:123], v[180:183], v[68:71]
	v_mfma_f32_16x16x32_bf16 v[60:63], v[116:119], v[184:187], v[60:63]
	v_mfma_f32_16x16x32_bf16 v[52:55], v[120:123], v[184:187], v[52:55]
	v_mfma_f32_16x16x32_bf16 v[44:47], v[116:119], v[196:199], v[44:47]
	v_mfma_f32_16x16x32_bf16 v[36:39], v[120:123], v[196:199], v[36:39]
	v_mfma_f32_16x16x32_bf16 v[24:27], v[116:119], v[216:219], v[24:27]
	v_mfma_f32_16x16x32_bf16 v[20:23], v[120:123], v[216:219], v[20:23]
	v_mfma_f32_16x16x32_bf16 v[76:79], v[140:143], v[188:191], v[76:79]
	v_mfma_f32_16x16x32_bf16 v[68:71], v[144:147], v[188:191], v[68:71]
	v_mfma_f32_16x16x32_bf16 v[60:63], v[140:143], v[192:195], v[60:63]
	v_mfma_f32_16x16x32_bf16 v[52:55], v[144:147], v[192:195], v[52:55]
	v_mfma_f32_16x16x32_bf16 v[44:47], v[140:143], v[220:223], v[44:47]
	v_mfma_f32_16x16x32_bf16 v[36:39], v[144:147], v[220:223], v[36:39]
	v_mfma_f32_16x16x32_bf16 v[24:27], v[140:143], v[224:227], v[24:27]
	v_mfma_f32_16x16x32_bf16 v[20:23], v[144:147], v[224:227], v[20:23]
	v_mfma_f32_16x16x32_bf16 v[80:83], v[164:167], v[180:183], v[80:83]
	v_mfma_f32_16x16x32_bf16 v[72:75], v[168:171], v[180:183], v[72:75]
	v_mfma_f32_16x16x32_bf16 v[64:67], v[164:167], v[184:187], v[64:67]
	v_mfma_f32_16x16x32_bf16 v[56:59], v[168:171], v[184:187], v[56:59]
	v_mfma_f32_16x16x32_bf16 v[48:51], v[164:167], v[196:199], v[48:51]
	v_mfma_f32_16x16x32_bf16 v[40:43], v[168:171], v[196:199], v[40:43]
	v_mfma_f32_16x16x32_bf16 v[28:31], v[164:167], v[216:219], v[28:31]
	v_mfma_f32_16x16x32_bf16 v[32:35], v[168:171], v[216:219], v[32:35]
	v_mfma_f32_16x16x32_bf16 v[80:83], v[172:175], v[188:191], v[80:83]
	v_mfma_f32_16x16x32_bf16 v[72:75], v[176:179], v[188:191], v[72:75]
	v_mfma_f32_16x16x32_bf16 v[64:67], v[172:175], v[192:195], v[64:67]
	v_mfma_f32_16x16x32_bf16 v[56:59], v[176:179], v[192:195], v[56:59]
	v_mfma_f32_16x16x32_bf16 v[48:51], v[172:175], v[220:223], v[48:51]
	v_mfma_f32_16x16x32_bf16 v[40:43], v[176:179], v[220:223], v[40:43]
	v_mfma_f32_16x16x32_bf16 v[28:31], v[172:175], v[224:227], v[28:31]
	v_mfma_f32_16x16x32_bf16 v[32:35], v[176:179], v[224:227], v[32:35]
	s_barrier
	s_add_i32 s85, 0, 0x18000
	v_add_u32_e32 v3, s85, v208
	v_add_u32_e32 v144, s85, v209
	s_add_i32 s85, 0, 0x1c000
	ds_read_b128 v[116:119], v3
	ds_read_b128 v[120:123], v3 offset:2048
	ds_read_b128 v[140:143], v144
	ds_read_b128 v[144:147], v144 offset:2048
	v_add_u32_e32 v3, s85, v208
	v_add_u32_e32 v176, s85, v209
	ds_read_b128 v[164:167], v3
	ds_read_b128 v[168:171], v3 offset:2048
	ds_read_b128 v[172:175], v176
	ds_read_b128 v[176:179], v176 offset:2048
	s_add_i32 s84, s84, s29
	s_mov_b32 m0, s39
	ds_read_b128 v[180:183], v214 offset:32768
	ds_read_b128 v[184:187], v214 offset:34816
	ds_read_b128 v[188:191], v215 offset:32768
	ds_read_b128 v[192:195], v215 offset:34816
	ds_read_b128 v[196:199], v214 offset:36864
	ds_read_b128 v[216:219], v214 offset:38912
	ds_read_b128 v[220:223], v215 offset:36864
	ds_read_b128 v[224:227], v215 offset:38912
	buffer_load_dwordx4 v204, s[48:51], s84 offen lds
	s_mov_b32 m0, s40
	s_nop 0
	buffer_load_dwordx4 v206, s[48:51], s84 offen lds
	s_waitcnt vmcnt(8)
	s_waitcnt lgkmcnt(0)
	s_barrier
	s_waitcnt lgkmcnt(0)
	v_mfma_f32_16x16x32_bf16 v[160:163], v[116:119], v[180:183], v[160:163]
	v_mfma_f32_16x16x32_bf16 v[152:155], v[120:123], v[180:183], v[152:155]
	v_mfma_f32_16x16x32_bf16 v[132:135], v[116:119], v[184:187], v[132:135]
	v_mfma_f32_16x16x32_bf16 v[124:127], v[120:123], v[184:187], v[124:127]
	v_mfma_f32_16x16x32_bf16 v[108:111], v[116:119], v[196:199], v[108:111]
	v_mfma_f32_16x16x32_bf16 v[100:103], v[120:123], v[196:199], v[100:103]
	v_mfma_f32_16x16x32_bf16 v[92:95], v[116:119], v[216:219], v[92:95]
	v_mfma_f32_16x16x32_bf16 v[84:87], v[120:123], v[216:219], v[84:87]
	v_mfma_f32_16x16x32_bf16 v[160:163], v[140:143], v[188:191], v[160:163]
	v_mfma_f32_16x16x32_bf16 v[152:155], v[144:147], v[188:191], v[152:155]
	v_mfma_f32_16x16x32_bf16 v[132:135], v[140:143], v[192:195], v[132:135]
	v_mfma_f32_16x16x32_bf16 v[124:127], v[144:147], v[192:195], v[124:127]
	v_mfma_f32_16x16x32_bf16 v[108:111], v[140:143], v[220:223], v[108:111]
	v_mfma_f32_16x16x32_bf16 v[100:103], v[144:147], v[220:223], v[100:103]
	v_mfma_f32_16x16x32_bf16 v[92:95], v[140:143], v[224:227], v[92:95]
	v_mfma_f32_16x16x32_bf16 v[84:87], v[144:147], v[224:227], v[84:87]
	v_mfma_f32_16x16x32_bf16 v[156:159], v[164:167], v[180:183], v[156:159]
	v_mfma_f32_16x16x32_bf16 v[148:151], v[168:171], v[180:183], v[148:151]
	v_mfma_f32_16x16x32_bf16 v[136:139], v[164:167], v[184:187], v[136:139]
	v_mfma_f32_16x16x32_bf16 v[128:131], v[168:171], v[184:187], v[128:131]
	v_mfma_f32_16x16x32_bf16 v[112:115], v[164:167], v[196:199], v[112:115]
	v_mfma_f32_16x16x32_bf16 v[104:107], v[168:171], v[196:199], v[104:107]
	v_mfma_f32_16x16x32_bf16 v[96:99], v[164:167], v[216:219], v[96:99]
	v_mfma_f32_16x16x32_bf16 v[88:91], v[168:171], v[216:219], v[88:91]
	v_mfma_f32_16x16x32_bf16 v[156:159], v[172:175], v[188:191], v[156:159]
	v_mfma_f32_16x16x32_bf16 v[148:151], v[176:179], v[188:191], v[148:151]
	v_mfma_f32_16x16x32_bf16 v[136:139], v[172:175], v[192:195], v[136:139]
	v_mfma_f32_16x16x32_bf16 v[128:131], v[176:179], v[192:195], v[128:131]
	v_mfma_f32_16x16x32_bf16 v[112:115], v[172:175], v[220:223], v[112:115]
	v_mfma_f32_16x16x32_bf16 v[104:107], v[176:179], v[220:223], v[104:107]
	v_mfma_f32_16x16x32_bf16 v[96:99], v[172:175], v[224:227], v[96:99]
	v_mfma_f32_16x16x32_bf16 v[88:91], v[176:179], v[224:227], v[88:91]
	s_barrier
	s_mov_b32 m0, s41
	ds_read_b128 v[180:183], v214 offset:49152
	ds_read_b128 v[184:187], v214 offset:51200
	ds_read_b128 v[188:191], v215 offset:49152
	ds_read_b128 v[192:195], v215 offset:51200
	ds_read_b128 v[196:199], v214 offset:53248
	ds_read_b128 v[216:219], v214 offset:55296
	ds_read_b128 v[220:223], v215 offset:53248
	ds_read_b128 v[224:227], v215 offset:55296
	buffer_load_dwordx4 v205, s[8:11], s82 offen lds
	s_mov_b32 m0, s42
	s_nop 0
	buffer_load_dwordx4 v207, s[8:11], s82 offen lds
	s_add_i32 s82, s82, s29
	s_mov_b32 m0, s45
	s_nop 0
	buffer_load_dwordx4 v205, s[8:11], s82 offen lds
	s_mov_b32 m0, s46
	s_nop 0
	buffer_load_dwordx4 v207, s[8:11], s82 offen lds
	s_mov_b32 m0, s43
	s_nop 0
	buffer_load_dwordx4 v204, s[48:51], s81 offen lds
	s_mov_b32 m0, s44
	s_nop 0
	buffer_load_dwordx4 v206, s[48:51], s81 offen lds
	s_waitcnt vmcnt(8)
	s_waitcnt lgkmcnt(0)
	s_barrier
	s_waitcnt lgkmcnt(0)
	v_mfma_f32_16x16x32_bf16 v[76:79], v[116:119], v[180:183], v[76:79]
	v_mfma_f32_16x16x32_bf16 v[68:71], v[120:123], v[180:183], v[68:71]
	v_mfma_f32_16x16x32_bf16 v[60:63], v[116:119], v[184:187], v[60:63]
	v_mfma_f32_16x16x32_bf16 v[52:55], v[120:123], v[184:187], v[52:55]
	v_mfma_f32_16x16x32_bf16 v[44:47], v[116:119], v[196:199], v[44:47]
	v_mfma_f32_16x16x32_bf16 v[36:39], v[120:123], v[196:199], v[36:39]
	v_mfma_f32_16x16x32_bf16 v[24:27], v[116:119], v[216:219], v[24:27]
	v_mfma_f32_16x16x32_bf16 v[20:23], v[120:123], v[216:219], v[20:23]
	v_mfma_f32_16x16x32_bf16 v[76:79], v[140:143], v[188:191], v[76:79]
	v_mfma_f32_16x16x32_bf16 v[68:71], v[144:147], v[188:191], v[68:71]
	v_mfma_f32_16x16x32_bf16 v[60:63], v[140:143], v[192:195], v[60:63]
	v_mfma_f32_16x16x32_bf16 v[52:55], v[144:147], v[192:195], v[52:55]
	v_mfma_f32_16x16x32_bf16 v[44:47], v[140:143], v[220:223], v[44:47]
	v_mfma_f32_16x16x32_bf16 v[36:39], v[144:147], v[220:223], v[36:39]
	v_mfma_f32_16x16x32_bf16 v[24:27], v[140:143], v[224:227], v[24:27]
	v_mfma_f32_16x16x32_bf16 v[20:23], v[144:147], v[224:227], v[20:23]
	v_mfma_f32_16x16x32_bf16 v[80:83], v[164:167], v[180:183], v[80:83]
	v_mfma_f32_16x16x32_bf16 v[72:75], v[168:171], v[180:183], v[72:75]
	v_mfma_f32_16x16x32_bf16 v[64:67], v[164:167], v[184:187], v[64:67]
	v_mfma_f32_16x16x32_bf16 v[56:59], v[168:171], v[184:187], v[56:59]
	v_mfma_f32_16x16x32_bf16 v[48:51], v[164:167], v[196:199], v[48:51]
	v_mfma_f32_16x16x32_bf16 v[40:43], v[168:171], v[196:199], v[40:43]
	v_mfma_f32_16x16x32_bf16 v[28:31], v[164:167], v[216:219], v[28:31]
	v_mfma_f32_16x16x32_bf16 v[32:35], v[168:171], v[216:219], v[32:35]
	v_mfma_f32_16x16x32_bf16 v[80:83], v[172:175], v[188:191], v[80:83]
	v_mfma_f32_16x16x32_bf16 v[72:75], v[176:179], v[188:191], v[72:75]
	v_mfma_f32_16x16x32_bf16 v[64:67], v[172:175], v[192:195], v[64:67]
	v_mfma_f32_16x16x32_bf16 v[56:59], v[176:179], v[192:195], v[56:59]
	v_mfma_f32_16x16x32_bf16 v[48:51], v[172:175], v[220:223], v[48:51]
	v_mfma_f32_16x16x32_bf16 v[40:43], v[176:179], v[220:223], v[40:43]
	v_mfma_f32_16x16x32_bf16 v[28:31], v[172:175], v[224:227], v[28:31]
	v_mfma_f32_16x16x32_bf16 v[32:35], v[176:179], v[224:227], v[32:35]
	s_barrier
